# v70 + the 4 remaining VALU address adds per K-loop iteration removed (LDS read bases precomputed per unit in spare VGPRs); K-loops now have no VALU besides MFMA
# speedup vs baseline: 1.0073x; 1.0014x over previous
; #define PG8_STAGE(bufoff, gbase, voff) do { _Pragma("unroll") for (int _i = 0; _i < 2; ++_i) \
;         __builtin_amdgcn_global_load_lds((const unsigned*)((const char*)(gbase) + (voff)[_i]), (PG8_LAS unsigned*)(lds + (bufoff) + ldsw + _i * 8192), 16, 0, 0); } while (0)
; #define PG8_LDA(dst, b, h) do { _Pragma("unroll") for (int m = 0; m < 4; ++m) _Pragma("unroll") for (int k = 0; k < 2; ++k) dst[m][k] = *(const PG8_LAS bf16x8*)(lds + PG8_SA(b, h) + aoff + m * 2048 + k * 1024); } while (0)
; #define PG8_LDB(dst, b, h) do { _Pragma("unroll") for (int n = 0; n < 2; ++n) _Pragma("unroll") for (int k = 0; k < 2; ++k) dst[n][k] = *(const PG8_LAS bf16x8*)(lds + PG8_SB(b, h) + boff + n * 2048 + k * 1024); } while (0)
; #define PG8_WAIT_V(n) asm volatile("s_waitcnt vmcnt(" #n ")" ::: "memory")
; #define PG8_WAIT_L(n) asm volatile("s_waitcnt lgkmcnt(" #n ")" ::: "memory")
; #define PG8_BAR __builtin_amdgcn_s_barrier()
; template <class Epi, class Sched, bool ALIGN_EPI = false, bool SP2 = false>
; __device__ __forceinline__ void gemm_phase(PG8_LAS unsigned char* lds, const Gemm g, const Sched& S, const Epi& E) {
;     ...
;         const bool has_next = S.next(ui + 1, nxt);
;         const char* nA = has_next ? (const char*)g.A + (size_t)nxt.pm * tstep : cA; const char* nB = has_next ? (const char*)g.Bt + (size_t)nxt.pn * tstep : cB;
;         for (int t = 0; t < nt; t += 2) {
;             const bool last = (t == nt - 2);
;             const char* a1 = cA + (size_t)(t + 1) * kstep;
;             const char* a2 = last ? nA : cA + (size_t)(t + 2) * kstep; const char* b2 = last ? nB : cB + (size_t)(t + 2) * kstep;
;             const char* a3 = a2 + kstep; const char* b3 = b2 + kstep;
;             if (last && has_next) S.a_ready(nxt);
;             if constexpr (SP2) {
;             PG8_LDB(B0, 0, 0); PG8_LDB(B1, 0, 1); PG8_SCHED; PG8_LDA(At, 0, 0); PG8_STAGE(PG8_SA(1, 1), a1 + hstep, voffA);
;             PG8_WAIT_V(8); PG8_WAIT_L(0); PG8_BAR; PG8_MMA(0, 0, At, B0); PG8_MMA(0, 1, At, B1); PG8_BAR; PG8_SCHED;
;     ...
; #pragma unroll
;         for (int a = 0; a < 2; ++a)
; #pragma unroll
;             for (int b = 0; b < 2; ++b)
; #pragma unroll
;                 for (int m = 0; m < 4; ++m)
; #pragma unroll
;                     for (int n = 0; n < 2; ++n) acc[a][b][m][n] = (f32x4){0.f, 0.f, 0.f, 0.f};
;         cur = nxt; cA = nA; cB = nB; ++ui;
.LBB0_138:
	s_ashr_i32 s25, s24, 31
	s_lshl_b64 s[0:1], s[24:25], 20
	s_add_u32 s0, s49, s0
	s_addc_u32 s1, s50, s1
	s_and_b64 s[28:29], s[42:43], exec
	s_cselect_b32 s25, s1, s31
	s_cselect_b32 s45, s0, s30
	s_ashr_i32 s23, s22, 31
	s_lshl_b64 s[28:29], s[22:23], 20
	s_add_u32 s28, s34, s28
	s_addc_u32 s29, s51, s29
	s_and_b64 s[38:39], s[42:43], exec
	s_cselect_b32 s23, s29, s37
	s_cselect_b32 s66, s28, s36
	s_add_u32 s30, s30, 0x80080
	s_addc_u32 s31, s31, 0
	s_add_u32 s67, s36, 0x100
	v_mov_b32_e32 v2, 0
	s_addc_u32 s68, s37, 0
	s_mov_b32 s69, -2
	v_mov_b32_e32 v3, v2
	v_mov_b32_e32 v4, v2
	v_mov_b32_e32 v5, v2
	v_mov_b32_e32 v6, v2
	v_mov_b32_e32 v7, v2
	v_mov_b32_e32 v8, v2
	v_mov_b32_e32 v9, v2
	v_mov_b32_e32 v18, v2
	v_mov_b32_e32 v19, v2
	v_mov_b32_e32 v20, v2
	v_mov_b32_e32 v21, v2
	v_mov_b32_e32 v22, v2
	v_mov_b32_e32 v23, v2
	v_mov_b32_e32 v24, v2
	v_mov_b32_e32 v25, v2
	v_mov_b32_e32 v34, v2
	v_mov_b32_e32 v35, v2
	v_mov_b32_e32 v36, v2
	v_mov_b32_e32 v37, v2
	v_mov_b32_e32 v38, v2
	v_mov_b32_e32 v39, v2
	v_mov_b32_e32 v40, v2
	v_mov_b32_e32 v41, v2
	v_mov_b32_e32 v50, v2
	v_mov_b32_e32 v51, v2
	v_mov_b32_e32 v52, v2
	v_mov_b32_e32 v53, v2
	v_mov_b32_e32 v54, v2
	v_mov_b32_e32 v55, v2
	v_mov_b32_e32 v56, v2
	v_mov_b32_e32 v57, v2
	v_mov_b32_e32 v10, v2
	v_mov_b32_e32 v11, v2
	v_mov_b32_e32 v12, v2
	v_mov_b32_e32 v13, v2
	v_mov_b32_e32 v14, v2
	v_mov_b32_e32 v15, v2
	v_mov_b32_e32 v16, v2
	v_mov_b32_e32 v17, v2
	v_mov_b32_e32 v26, v2
	v_mov_b32_e32 v27, v2
	v_mov_b32_e32 v28, v2
	v_mov_b32_e32 v29, v2
	v_mov_b32_e32 v30, v2
	v_mov_b32_e32 v31, v2
	v_mov_b32_e32 v32, v2
	v_mov_b32_e32 v33, v2
	v_mov_b32_e32 v42, v2
	v_mov_b32_e32 v43, v2
	v_mov_b32_e32 v44, v2
	v_mov_b32_e32 v45, v2
	v_mov_b32_e32 v46, v2
	v_mov_b32_e32 v47, v2
	v_mov_b32_e32 v48, v2
	v_mov_b32_e32 v49, v2
	v_mov_b32_e32 v58, v2
	v_mov_b32_e32 v59, v2
	v_mov_b32_e32 v60, v2
	v_mov_b32_e32 v61, v2
	v_mov_b32_e32 v62, v2
	v_mov_b32_e32 v63, v2
	v_mov_b32_e32 v64, v2
	v_mov_b32_e32 v65, v2
	v_mov_b32_e32 v66, v2
	v_mov_b32_e32 v67, v2
	v_mov_b32_e32 v68, v2
	v_mov_b32_e32 v69, v2
	v_mov_b32_e32 v70, v2
	v_mov_b32_e32 v71, v2
	v_mov_b32_e32 v72, v2
	v_mov_b32_e32 v73, v2
	v_mov_b32_e32 v82, v2
	v_mov_b32_e32 v83, v2
	v_mov_b32_e32 v84, v2
	v_mov_b32_e32 v85, v2
	v_mov_b32_e32 v86, v2
	v_mov_b32_e32 v87, v2
	v_mov_b32_e32 v88, v2
	v_mov_b32_e32 v89, v2
	v_mov_b32_e32 v98, v2
	v_mov_b32_e32 v99, v2
	v_mov_b32_e32 v100, v2
	v_mov_b32_e32 v101, v2
	v_mov_b32_e32 v102, v2
	v_mov_b32_e32 v103, v2
	v_mov_b32_e32 v104, v2
	v_mov_b32_e32 v105, v2
	v_mov_b32_e32 v114, v2
	v_mov_b32_e32 v115, v2
	v_mov_b32_e32 v116, v2
	v_mov_b32_e32 v117, v2
	v_mov_b32_e32 v118, v2
	v_mov_b32_e32 v119, v2
	v_mov_b32_e32 v120, v2
	v_mov_b32_e32 v121, v2
	v_mov_b32_e32 v74, v2
	v_mov_b32_e32 v75, v2
	v_mov_b32_e32 v76, v2
	v_mov_b32_e32 v77, v2
	v_mov_b32_e32 v78, v2
	v_mov_b32_e32 v79, v2
	v_mov_b32_e32 v80, v2
	v_mov_b32_e32 v81, v2
	v_mov_b32_e32 v90, v2
	v_mov_b32_e32 v91, v2
	v_mov_b32_e32 v92, v2
	v_mov_b32_e32 v93, v2
	v_mov_b32_e32 v94, v2
	v_mov_b32_e32 v95, v2
	v_mov_b32_e32 v96, v2
	v_mov_b32_e32 v97, v2
	v_mov_b32_e32 v106, v2
	v_mov_b32_e32 v107, v2
	v_mov_b32_e32 v108, v2
	v_mov_b32_e32 v109, v2
	v_mov_b32_e32 v110, v2
	v_mov_b32_e32 v111, v2
	v_mov_b32_e32 v112, v2
	v_mov_b32_e32 v113, v2
	v_mov_b32_e32 v122, v2
	v_mov_b32_e32 v123, v2
	v_mov_b32_e32 v124, v2
	v_mov_b32_e32 v125, v2
	v_mov_b32_e32 v126, v2
	v_mov_b32_e32 v127, v2
	v_mov_b32_e32 v128, v2
	v_mov_b32_e32 v129, v2
	v_add_u32_e32 v244, 0x10000, v148
	v_add_u32_e32 v245, 0x14000, v148
	v_add_u32_e32 v246, 0x18000, v148
	v_add_u32_e32 v247, 0x1c000, v148
.LBB0_139:
	s_add_u32 s36, s30, 0xfff80080
	s_addc_u32 s37, s31, -1
	s_add_i32 s70, 0, 0x10000
	s_cmp_eq_u32 s69, 28
	s_cselect_b32 s39, s25, s37
	s_cselect_b32 s38, s45, s36
	s_cselect_b32 s37, s23, s68
	s_cselect_b32 s36, s66, s67
	s_add_i32 s75, 0, 0x14000
	ds_read_b128 v[152:155], v244
	ds_read_b128 v[166:169], v244 offset:1024
	ds_read_b128 v[170:173], v244 offset:2048
	ds_read_b128 v[174:177], v244 offset:3072
	ds_read_b128 v[178:181], v245
	ds_read_b128 v[182:185], v245 offset:1024
	ds_read_b128 v[186:189], v245 offset:2048
	ds_read_b128 v[190:193], v245 offset:3072
	s_add_u32 s98, s30, 0xfff80000
	s_addc_u32 s99, s31, -1
	s_mov_b32 m0, s57
	s_nop 0
	global_load_lds_dwordx4 v138, s[98:99]
	s_mov_b32 m0, s58
	s_nop 0
	global_load_lds_dwordx4 v140, s[98:99]
	s_add_i32 m0, s53, 0xc000
	ds_read_b128 v[200:203], v151
	ds_read_b128 v[204:207], v151 offset:1024
	ds_read_b128 v[208:211], v151 offset:2048
	ds_read_b128 v[212:215], v151 offset:3072
	ds_read_b128 v[216:219], v151 offset:4096
	ds_read_b128 v[220:223], v151 offset:5120
	ds_read_b128 v[224:227], v151 offset:6144
	ds_read_b128 v[228:231], v151 offset:7168
	global_load_lds_dwordx4 v138, s[30:31]
	s_add_i32 m0, s53, 0xe000
	s_nop 0
	global_load_lds_dwordx4 v140, s[30:31]
	s_waitcnt vmcnt(8)
	s_waitcnt lgkmcnt(0)
	s_barrier
; #define PG8_STAGE(bufoff, gbase, voff) do { _Pragma("unroll") for (int _i = 0; _i < 2; ++_i) \
;         __builtin_amdgcn_global_load_lds((const unsigned*)((const char*)(gbase) + (voff)[_i]), (PG8_LAS unsigned*)(lds + (bufoff) + ldsw + _i * 8192), 16, 0, 0); } while (0)
; #define PG8_LDA(dst, b, h) do { _Pragma("unroll") for (int m = 0; m < 4; ++m) _Pragma("unroll") for (int k = 0; k < 2; ++k) dst[m][k] = *(const PG8_LAS bf16x8*)(lds + PG8_SA(b, h) + aoff + m * 2048 + k * 1024); } while (0)
; #define PG8_LDB(dst, b, h) do { _Pragma("unroll") for (int n = 0; n < 2; ++n) _Pragma("unroll") for (int k = 0; k < 2; ++k) dst[n][k] = *(const PG8_LAS bf16x8*)(lds + PG8_SB(b, h) + boff + n * 2048 + k * 1024); } while (0)
; #define PG8_MMA(ai, bj, At, Bt) do { __builtin_amdgcn_s_setprio(1); _Pragma("unroll") for (int m = 0; m < 4; ++m) _Pragma("unroll") for (int n = 0; n < 2; ++n) _Pragma("unroll") for (int k = 0; k < 2; ++k) \
;         acc[ai][bj][m][n] = __builtin_amdgcn_mfma_f32_16x16x32_bf16(Bt[n][k], At[m][k], acc[ai][bj][m][n], 0, 0, 0); __builtin_amdgcn_s_setprio(0); } while (0)
; #define PG8_WAIT_V(n) asm volatile("s_waitcnt vmcnt(" #n ")" ::: "memory")
; #define PG8_WAIT_L(n) asm volatile("s_waitcnt lgkmcnt(" #n ")" ::: "memory")
; #define PG8_BAR __builtin_amdgcn_s_barrier()
; #define PG8_SCHED __builtin_amdgcn_sched_barrier(0)
; template <class Epi, class Sched, bool ALIGN_EPI = false, bool SP2 = false>
; __device__ __forceinline__ void gemm_phase(PG8_LAS unsigned char* lds, const Gemm g, const Sched& S, const Epi& E) {
;     ...
;             PG8_WAIT_V(8); PG8_WAIT_L(0); PG8_BAR; PG8_MMA(0, 0, At, B0); PG8_MMA(0, 1, At, B1); PG8_BAR; PG8_SCHED;
;             PG8_LDA(At, 0, 1); PG8_STAGE(PG8_SB(0, 0), b2, voffB); PG8_STAGE(PG8_SB(0, 1), b2 + hstep, voffB); PG8_STAGE(PG8_SA(0, 0), a2, voffA);
;             PG8_WAIT_V(8); PG8_WAIT_L(0); PG8_BAR; PG8_MMA(1, 0, At, B0); PG8_MMA(1, 1, At, B1); PG8_BAR; PG8_SCHED;
;             PG8_LDB(B0, 1, 0); PG8_LDB(B1, 1, 1); PG8_SCHED; PG8_LDA(At, 1, 0); PG8_STAGE(PG8_SA(0, 1), a2 + hstep, voffA);
	s_waitcnt lgkmcnt(0)
	v_mfma_f32_16x16x32_bf16 v[126:129], v[152:155], v[200:203], v[126:129]
	v_mfma_f32_16x16x32_bf16 v[122:125], v[170:173], v[200:203], v[122:125]
	v_mfma_f32_16x16x32_bf16 v[110:113], v[152:155], v[208:211], v[110:113]
	v_mfma_f32_16x16x32_bf16 v[106:109], v[170:173], v[208:211], v[106:109]
	v_mfma_f32_16x16x32_bf16 v[94:97], v[152:155], v[216:219], v[94:97]
	v_mfma_f32_16x16x32_bf16 v[90:93], v[170:173], v[216:219], v[90:93]
	v_mfma_f32_16x16x32_bf16 v[78:81], v[152:155], v[224:227], v[78:81]
	v_mfma_f32_16x16x32_bf16 v[74:77], v[170:173], v[224:227], v[74:77]
	v_mfma_f32_16x16x32_bf16 v[126:129], v[166:169], v[204:207], v[126:129]
	v_mfma_f32_16x16x32_bf16 v[122:125], v[174:177], v[204:207], v[122:125]
	v_mfma_f32_16x16x32_bf16 v[110:113], v[166:169], v[212:215], v[110:113]
	v_mfma_f32_16x16x32_bf16 v[106:109], v[174:177], v[212:215], v[106:109]
	v_mfma_f32_16x16x32_bf16 v[94:97], v[166:169], v[220:223], v[94:97]
	v_mfma_f32_16x16x32_bf16 v[90:93], v[174:177], v[220:223], v[90:93]
	v_mfma_f32_16x16x32_bf16 v[78:81], v[166:169], v[228:231], v[78:81]
	v_mfma_f32_16x16x32_bf16 v[74:77], v[174:177], v[228:231], v[74:77]
	v_mfma_f32_16x16x32_bf16 v[118:121], v[178:181], v[200:203], v[118:121]
	v_mfma_f32_16x16x32_bf16 v[114:117], v[186:189], v[200:203], v[114:117]
	v_mfma_f32_16x16x32_bf16 v[102:105], v[178:181], v[208:211], v[102:105]
	v_mfma_f32_16x16x32_bf16 v[98:101], v[186:189], v[208:211], v[98:101]
	v_mfma_f32_16x16x32_bf16 v[86:89], v[178:181], v[216:219], v[86:89]
	v_mfma_f32_16x16x32_bf16 v[82:85], v[186:189], v[216:219], v[82:85]
	v_mfma_f32_16x16x32_bf16 v[70:73], v[178:181], v[224:227], v[70:73]
	v_mfma_f32_16x16x32_bf16 v[66:69], v[186:189], v[224:227], v[66:69]
	v_mfma_f32_16x16x32_bf16 v[118:121], v[182:185], v[204:207], v[118:121]
	v_mfma_f32_16x16x32_bf16 v[114:117], v[190:193], v[204:207], v[114:117]
	v_mfma_f32_16x16x32_bf16 v[102:105], v[182:185], v[212:215], v[102:105]
	v_mfma_f32_16x16x32_bf16 v[98:101], v[190:193], v[212:215], v[98:101]
	v_mfma_f32_16x16x32_bf16 v[86:89], v[182:185], v[220:223], v[86:89]
	v_mfma_f32_16x16x32_bf16 v[82:85], v[190:193], v[220:223], v[82:85]
	v_mfma_f32_16x16x32_bf16 v[70:73], v[182:185], v[228:231], v[70:73]
	v_mfma_f32_16x16x32_bf16 v[66:69], v[190:193], v[228:231], v[66:69]
	s_barrier
	s_add_i32 s70, s70, s52
	s_mov_b32 m0, s70
	ds_read_b128 v[200:203], v151 offset:16384
	ds_read_b128 v[204:207], v151 offset:17408
	ds_read_b128 v[208:211], v151 offset:18432
	ds_read_b128 v[212:215], v151 offset:19456
	ds_read_b128 v[216:219], v151 offset:20480
	ds_read_b128 v[220:223], v151 offset:21504
	ds_read_b128 v[224:227], v151 offset:22528
	ds_read_b128 v[228:231], v151 offset:23552
	global_load_lds_dwordx4 v158, s[36:37]
	s_add_i32 m0, s70, 0x2000
	s_add_u32 s70, s36, 0x80000
	s_addc_u32 s71, s37, 0
	s_add_i32 s75, s75, s52
	global_load_lds_dwordx4 v134, s[36:37]
	s_mov_b32 m0, s75
	s_nop 0
	global_load_lds_dwordx4 v158, s[70:71]
	s_add_i32 m0, s75, 0x2000
	s_nop 0
	global_load_lds_dwordx4 v134, s[70:71]
	s_waitcnt vmcnt(6)
	s_waitcnt lgkmcnt(0)
	s_barrier
	s_waitcnt lgkmcnt(0)
	v_mfma_f32_16x16x32_bf16 v[62:65], v[152:155], v[200:203], v[62:65]
	v_mfma_f32_16x16x32_bf16 v[58:61], v[170:173], v[200:203], v[58:61]
	v_mfma_f32_16x16x32_bf16 v[46:49], v[152:155], v[208:211], v[46:49]
	v_mfma_f32_16x16x32_bf16 v[42:45], v[170:173], v[208:211], v[42:45]
	v_mfma_f32_16x16x32_bf16 v[30:33], v[152:155], v[216:219], v[30:33]
	v_mfma_f32_16x16x32_bf16 v[26:29], v[170:173], v[216:219], v[26:29]
	v_mfma_f32_16x16x32_bf16 v[14:17], v[152:155], v[224:227], v[14:17]
	v_mfma_f32_16x16x32_bf16 v[10:13], v[170:173], v[224:227], v[10:13]
	v_mfma_f32_16x16x32_bf16 v[62:65], v[166:169], v[204:207], v[62:65]
	v_mfma_f32_16x16x32_bf16 v[58:61], v[174:177], v[204:207], v[58:61]
	v_mfma_f32_16x16x32_bf16 v[46:49], v[166:169], v[212:215], v[46:49]
	v_mfma_f32_16x16x32_bf16 v[42:45], v[174:177], v[212:215], v[42:45]
	v_mfma_f32_16x16x32_bf16 v[30:33], v[166:169], v[220:223], v[30:33]
	v_mfma_f32_16x16x32_bf16 v[26:29], v[174:177], v[220:223], v[26:29]
	v_mfma_f32_16x16x32_bf16 v[14:17], v[166:169], v[228:231], v[14:17]
	v_mfma_f32_16x16x32_bf16 v[10:13], v[174:177], v[228:231], v[10:13]
	v_mfma_f32_16x16x32_bf16 v[54:57], v[178:181], v[200:203], v[54:57]
	v_mfma_f32_16x16x32_bf16 v[50:53], v[186:189], v[200:203], v[50:53]
	v_mfma_f32_16x16x32_bf16 v[38:41], v[178:181], v[208:211], v[38:41]
	v_mfma_f32_16x16x32_bf16 v[34:37], v[186:189], v[208:211], v[34:37]
	v_mfma_f32_16x16x32_bf16 v[22:25], v[178:181], v[216:219], v[22:25]
	v_mfma_f32_16x16x32_bf16 v[18:21], v[186:189], v[216:219], v[18:21]
	v_mfma_f32_16x16x32_bf16 v[6:9], v[178:181], v[224:227], v[6:9]
	v_mfma_f32_16x16x32_bf16 v[2:5], v[186:189], v[224:227], v[2:5]
	v_mfma_f32_16x16x32_bf16 v[54:57], v[182:185], v[204:207], v[54:57]
	v_mfma_f32_16x16x32_bf16 v[50:53], v[190:193], v[204:207], v[50:53]
	v_mfma_f32_16x16x32_bf16 v[38:41], v[182:185], v[212:215], v[38:41]
	v_mfma_f32_16x16x32_bf16 v[34:37], v[190:193], v[212:215], v[34:37]
	v_mfma_f32_16x16x32_bf16 v[22:25], v[182:185], v[220:223], v[22:25]
	v_mfma_f32_16x16x32_bf16 v[18:21], v[190:193], v[220:223], v[18:21]
	v_mfma_f32_16x16x32_bf16 v[6:9], v[182:185], v[228:231], v[6:9]
	v_mfma_f32_16x16x32_bf16 v[2:5], v[190:193], v[228:231], v[2:5]
	s_barrier
; #define PG8_STAGE(bufoff, gbase, voff) do { _Pragma("unroll") for (int _i = 0; _i < 2; ++_i) \
;         __builtin_amdgcn_global_load_lds((const unsigned*)((const char*)(gbase) + (voff)[_i]), (PG8_LAS unsigned*)(lds + (bufoff) + ldsw + _i * 8192), 16, 0, 0); } while (0)
; #define PG8_LDA(dst, b, h) do { _Pragma("unroll") for (int m = 0; m < 4; ++m) _Pragma("unroll") for (int k = 0; k < 2; ++k) dst[m][k] = *(const PG8_LAS bf16x8*)(lds + PG8_SA(b, h) + aoff + m * 2048 + k * 1024); } while (0)
; #define PG8_LDB(dst, b, h) do { _Pragma("unroll") for (int n = 0; n < 2; ++n) _Pragma("unroll") for (int k = 0; k < 2; ++k) dst[n][k] = *(const PG8_LAS bf16x8*)(lds + PG8_SB(b, h) + boff + n * 2048 + k * 1024); } while (0)
; #define PG8_MMA(ai, bj, At, Bt) do { __builtin_amdgcn_s_setprio(1); _Pragma("unroll") for (int m = 0; m < 4; ++m) _Pragma("unroll") for (int n = 0; n < 2; ++n) _Pragma("unroll") for (int k = 0; k < 2; ++k) \
;         acc[ai][bj][m][n] = __builtin_amdgcn_mfma_f32_16x16x32_bf16(Bt[n][k], At[m][k], acc[ai][bj][m][n], 0, 0, 0); __builtin_amdgcn_s_setprio(0); } while (0)
; #define PG8_WAIT_V(n) asm volatile("s_waitcnt vmcnt(" #n ")" ::: "memory")
; #define PG8_WAIT_L(n) asm volatile("s_waitcnt lgkmcnt(" #n ")" ::: "memory")
; #define PG8_BAR __builtin_amdgcn_s_barrier()
; #define PG8_SCHED __builtin_amdgcn_sched_barrier(0)
; template <class Epi, class Sched, bool ALIGN_EPI = false, bool SP2 = false>
; __device__ __forceinline__ void gemm_phase(PG8_LAS unsigned char* lds, const Gemm g, const Sched& S, const Epi& E) {
;     ...
;             PG8_LDB(B0, 1, 0); PG8_LDB(B1, 1, 1); PG8_SCHED; PG8_LDA(At, 1, 0); PG8_STAGE(PG8_SA(0, 1), a2 + hstep, voffA);
;             PG8_WAIT_V(8); PG8_WAIT_L(0); PG8_BAR; PG8_MMA(0, 0, At, B0); PG8_MMA(0, 1, At, B1); PG8_BAR; PG8_SCHED;
;             PG8_LDA(At, 1, 1); PG8_STAGE(PG8_SB(1, 0), b3, voffB); PG8_STAGE(PG8_SB(1, 1), b3 + hstep, voffB); PG8_STAGE(PG8_SA(1, 0), a3, voffA);
;             PG8_WAIT_V(8); PG8_WAIT_L(0); PG8_BAR; PG8_MMA(1, 0, At, B0); PG8_MMA(1, 1, At, B1); PG8_BAR; PG8_SCHED;
	s_add_i32 s70, 0, 0x18000
	s_add_i32 s71, 0, 0x1c000
	ds_read_b128 v[152:155], v246
	ds_read_b128 v[166:169], v246 offset:1024
	ds_read_b128 v[170:173], v246 offset:2048
	ds_read_b128 v[174:177], v246 offset:3072
	ds_read_b128 v[178:181], v247
	ds_read_b128 v[182:185], v247 offset:1024
	ds_read_b128 v[186:189], v247 offset:2048
	ds_read_b128 v[190:193], v247 offset:3072
	s_mov_b32 m0, s53
	s_nop 0
	global_load_lds_dwordx4 v130, s[38:39]
	s_mov_b32 m0, s54
	s_nop 0
	global_load_lds_dwordx4 v132, s[38:39]
	s_add_u32 s38, s38, 0x80000
	s_addc_u32 s39, s39, 0
	s_mov_b32 m0, s55
	ds_read_b128 v[200:203], v151 offset:32768
	ds_read_b128 v[204:207], v151 offset:33792
	ds_read_b128 v[208:211], v151 offset:34816
	ds_read_b128 v[212:215], v151 offset:35840
	ds_read_b128 v[216:219], v151 offset:36864
	ds_read_b128 v[220:223], v151 offset:37888
	ds_read_b128 v[224:227], v151 offset:38912
	ds_read_b128 v[228:231], v151 offset:39936
	global_load_lds_dwordx4 v130, s[38:39]
	s_mov_b32 m0, s56
	s_nop 0
	global_load_lds_dwordx4 v132, s[38:39]
	s_waitcnt vmcnt(8)
	s_waitcnt lgkmcnt(0)
	s_barrier
	s_waitcnt lgkmcnt(0)
	v_mfma_f32_16x16x32_bf16 v[126:129], v[152:155], v[200:203], v[126:129]
	v_mfma_f32_16x16x32_bf16 v[122:125], v[170:173], v[200:203], v[122:125]
	v_mfma_f32_16x16x32_bf16 v[110:113], v[152:155], v[208:211], v[110:113]
	v_mfma_f32_16x16x32_bf16 v[106:109], v[170:173], v[208:211], v[106:109]
	v_mfma_f32_16x16x32_bf16 v[94:97], v[152:155], v[216:219], v[94:97]
	v_mfma_f32_16x16x32_bf16 v[90:93], v[170:173], v[216:219], v[90:93]
	v_mfma_f32_16x16x32_bf16 v[78:81], v[152:155], v[224:227], v[78:81]
	v_mfma_f32_16x16x32_bf16 v[74:77], v[170:173], v[224:227], v[74:77]
	v_mfma_f32_16x16x32_bf16 v[126:129], v[166:169], v[204:207], v[126:129]
	v_mfma_f32_16x16x32_bf16 v[122:125], v[174:177], v[204:207], v[122:125]
	v_mfma_f32_16x16x32_bf16 v[110:113], v[166:169], v[212:215], v[110:113]
	v_mfma_f32_16x16x32_bf16 v[106:109], v[174:177], v[212:215], v[106:109]
	v_mfma_f32_16x16x32_bf16 v[94:97], v[166:169], v[220:223], v[94:97]
	v_mfma_f32_16x16x32_bf16 v[90:93], v[174:177], v[220:223], v[90:93]
	v_mfma_f32_16x16x32_bf16 v[78:81], v[166:169], v[228:231], v[78:81]
	v_mfma_f32_16x16x32_bf16 v[74:77], v[174:177], v[228:231], v[74:77]
	v_mfma_f32_16x16x32_bf16 v[118:121], v[178:181], v[200:203], v[118:121]
	v_mfma_f32_16x16x32_bf16 v[114:117], v[186:189], v[200:203], v[114:117]
	v_mfma_f32_16x16x32_bf16 v[102:105], v[178:181], v[208:211], v[102:105]
	v_mfma_f32_16x16x32_bf16 v[98:101], v[186:189], v[208:211], v[98:101]
	v_mfma_f32_16x16x32_bf16 v[86:89], v[178:181], v[216:219], v[86:89]
	v_mfma_f32_16x16x32_bf16 v[82:85], v[186:189], v[216:219], v[82:85]
	v_mfma_f32_16x16x32_bf16 v[70:73], v[178:181], v[224:227], v[70:73]
	v_mfma_f32_16x16x32_bf16 v[66:69], v[186:189], v[224:227], v[66:69]
	v_mfma_f32_16x16x32_bf16 v[118:121], v[182:185], v[204:207], v[118:121]
	v_mfma_f32_16x16x32_bf16 v[114:117], v[190:193], v[204:207], v[114:117]
	v_mfma_f32_16x16x32_bf16 v[102:105], v[182:185], v[212:215], v[102:105]
	v_mfma_f32_16x16x32_bf16 v[98:101], v[190:193], v[212:215], v[98:101]
	v_mfma_f32_16x16x32_bf16 v[86:89], v[182:185], v[220:223], v[86:89]
	v_mfma_f32_16x16x32_bf16 v[82:85], v[190:193], v[220:223], v[82:85]
	v_mfma_f32_16x16x32_bf16 v[70:73], v[182:185], v[228:231], v[70:73]
	v_mfma_f32_16x16x32_bf16 v[66:69], v[190:193], v[228:231], v[66:69]
	s_barrier
	s_add_i32 s38, s70, s52
	s_add_i32 m0, s38, 0xffffff80
	ds_read_b128 v[200:203], v151 offset:49152
	ds_read_b128 v[204:207], v151 offset:50176
	ds_read_b128 v[208:211], v151 offset:51200
	ds_read_b128 v[212:215], v151 offset:52224
	ds_read_b128 v[216:219], v151 offset:53248
	ds_read_b128 v[220:223], v151 offset:54272
	ds_read_b128 v[224:227], v151 offset:55296
	ds_read_b128 v[228:231], v151 offset:56320
	global_load_lds_dwordx4 v158, s[36:37] offset:128
	s_add_i32 m0, s38, 0x1f80
	s_add_i32 s38, s71, s52
	global_load_lds_dwordx4 v134, s[36:37] offset:128
	s_add_u32 s36, s36, 0x80080
	s_addc_u32 s37, s37, 0
	s_mov_b32 m0, s38
	s_nop 0
	global_load_lds_dwordx4 v158, s[36:37]
	s_add_i32 m0, s38, 0x2000
	s_nop 0
	global_load_lds_dwordx4 v134, s[36:37]
	s_waitcnt vmcnt(6)
	s_waitcnt lgkmcnt(0)
	s_barrier
	s_waitcnt lgkmcnt(0)
	v_mfma_f32_16x16x32_bf16 v[62:65], v[152:155], v[200:203], v[62:65]
	v_mfma_f32_16x16x32_bf16 v[58:61], v[170:173], v[200:203], v[58:61]
	v_mfma_f32_16x16x32_bf16 v[46:49], v[152:155], v[208:211], v[46:49]
	v_mfma_f32_16x16x32_bf16 v[42:45], v[170:173], v[208:211], v[42:45]
	v_mfma_f32_16x16x32_bf16 v[30:33], v[152:155], v[216:219], v[30:33]
	v_mfma_f32_16x16x32_bf16 v[26:29], v[170:173], v[216:219], v[26:29]
	v_mfma_f32_16x16x32_bf16 v[14:17], v[152:155], v[224:227], v[14:17]
	v_mfma_f32_16x16x32_bf16 v[10:13], v[170:173], v[224:227], v[10:13]
	v_mfma_f32_16x16x32_bf16 v[62:65], v[166:169], v[204:207], v[62:65]
	v_mfma_f32_16x16x32_bf16 v[58:61], v[174:177], v[204:207], v[58:61]
	v_mfma_f32_16x16x32_bf16 v[46:49], v[166:169], v[212:215], v[46:49]
	v_mfma_f32_16x16x32_bf16 v[42:45], v[174:177], v[212:215], v[42:45]
	v_mfma_f32_16x16x32_bf16 v[30:33], v[166:169], v[220:223], v[30:33]
	v_mfma_f32_16x16x32_bf16 v[26:29], v[174:177], v[220:223], v[26:29]
	v_mfma_f32_16x16x32_bf16 v[14:17], v[166:169], v[228:231], v[14:17]
	v_mfma_f32_16x16x32_bf16 v[10:13], v[174:177], v[228:231], v[10:13]
	v_mfma_f32_16x16x32_bf16 v[54:57], v[178:181], v[200:203], v[54:57]
	v_mfma_f32_16x16x32_bf16 v[50:53], v[186:189], v[200:203], v[50:53]
	v_mfma_f32_16x16x32_bf16 v[38:41], v[178:181], v[208:211], v[38:41]
	v_mfma_f32_16x16x32_bf16 v[34:37], v[186:189], v[208:211], v[34:37]
	v_mfma_f32_16x16x32_bf16 v[22:25], v[178:181], v[216:219], v[22:25]
	v_mfma_f32_16x16x32_bf16 v[18:21], v[186:189], v[216:219], v[18:21]
	v_mfma_f32_16x16x32_bf16 v[6:9], v[178:181], v[224:227], v[6:9]
	v_mfma_f32_16x16x32_bf16 v[2:5], v[186:189], v[224:227], v[2:5]
	v_mfma_f32_16x16x32_bf16 v[54:57], v[182:185], v[204:207], v[54:57]
	v_mfma_f32_16x16x32_bf16 v[50:53], v[190:193], v[204:207], v[50:53]
	v_mfma_f32_16x16x32_bf16 v[38:41], v[182:185], v[212:215], v[38:41]
	v_mfma_f32_16x16x32_bf16 v[34:37], v[190:193], v[212:215], v[34:37]
	v_mfma_f32_16x16x32_bf16 v[22:25], v[182:185], v[220:223], v[22:25]
	v_mfma_f32_16x16x32_bf16 v[18:21], v[190:193], v[220:223], v[18:21]
	v_mfma_f32_16x16x32_bf16 v[6:9], v[182:185], v[228:231], v[6:9]
	v_mfma_f32_16x16x32_bf16 v[2:5], v[190:193], v[228:231], v[2:5]
	s_barrier
	s_add_i32 s69, s69, 2
	s_add_u32 s30, s30, 0x100
	s_addc_u32 s31, s31, 0
	s_add_u32 s67, s67, 0x100
	s_addc_u32 s68, s68, 0
	s_cmp_gt_u32 s69, 29
	s_cbranch_scc0 .LBB0_139
	s_and_b64 vcc, exec, s[16:17]
	s_cbranch_vccz .LBB0_142
	s_barrier

; #define PG8_STAGE(bufoff, gbase, voff) do { _Pragma("unroll") for (int _i = 0; _i < 2; ++_i) \
;         __builtin_amdgcn_global_load_lds((const unsigned*)((const char*)(gbase) + (voff)[_i]), (PG8_LAS unsigned*)(lds + (bufoff) + ldsw + _i * 8192), 16, 0, 0); } while (0)
; #define PG8_LDA(dst, b, h) do { _Pragma("unroll") for (int m = 0; m < 4; ++m) _Pragma("unroll") for (int k = 0; k < 2; ++k) dst[m][k] = *(const PG8_LAS bf16x8*)(lds + PG8_SA(b, h) + aoff + m * 2048 + k * 1024); } while (0)
; #define PG8_LDB(dst, b, h) do { _Pragma("unroll") for (int n = 0; n < 2; ++n) _Pragma("unroll") for (int k = 0; k < 2; ++k) dst[n][k] = *(const PG8_LAS bf16x8*)(lds + PG8_SB(b, h) + boff + n * 2048 + k * 1024); } while (0)
; #define PG8_WAIT_V(n) asm volatile("s_waitcnt vmcnt(" #n ")" ::: "memory")
; #define PG8_WAIT_L(n) asm volatile("s_waitcnt lgkmcnt(" #n ")" ::: "memory")
; #define PG8_BAR __builtin_amdgcn_s_barrier()
; template <class Epi, class Sched, bool ALIGN_EPI = false, bool SP2 = false>
; __device__ __forceinline__ void gemm_phase(PG8_LAS unsigned char* lds, const Gemm g, const Sched& S, const Epi& E) {
;     ...
;         const bool has_next = S.next(ui + 1, nxt);
;         const char* nA = has_next ? (const char*)g.A + (size_t)nxt.pm * tstep : cA; const char* nB = has_next ? (const char*)g.Bt + (size_t)nxt.pn * tstep : cB;
;         for (int t = 0; t < nt; t += 2) {
;             const bool last = (t == nt - 2);
;             const char* a1 = cA + (size_t)(t + 1) * kstep;
;             const char* a2 = last ? nA : cA + (size_t)(t + 2) * kstep; const char* b2 = last ? nB : cB + (size_t)(t + 2) * kstep;
;             const char* a3 = a2 + kstep; const char* b3 = b2 + kstep;
;             if (last && has_next) S.a_ready(nxt);
;             if constexpr (SP2) {
;             PG8_LDB(B0, 0, 0); PG8_LDB(B1, 0, 1); PG8_SCHED; PG8_LDA(At, 0, 0); PG8_STAGE(PG8_SA(1, 1), a1 + hstep, voffA);
;             PG8_WAIT_V(8); PG8_WAIT_L(0); PG8_BAR; PG8_MMA(0, 0, At, B0); PG8_MMA(0, 1, At, B1); PG8_BAR; PG8_SCHED;
;     ...
; #pragma unroll
;         for (int a = 0; a < 2; ++a)
; #pragma unroll
;             for (int b = 0; b < 2; ++b)
; #pragma unroll
;                 for (int m = 0; m < 4; ++m)
; #pragma unroll
;                     for (int n = 0; n < 2; ++n) acc[a][b][m][n] = (f32x4){0.f, 0.f, 0.f, 0.f};
;         cur = nxt; cA = nA; cB = nB; ++ui;
.LBB0_666:
	s_ashr_i32 s23, s22, 31
	s_lshl_b64 s[24:25], s[22:23], 20
	s_add_u32 s24, s21, s24
	s_addc_u32 s25, s38, s25
	s_and_b64 s[28:29], s[44:45], exec
	s_cselect_b32 s23, s25, s1
	s_cselect_b32 s59, s24, s0
	s_ashr_i32 s19, s18, 31
	s_lshl_b64 s[28:29], s[18:19], 20
	s_add_u32 s28, s39, s28
	s_addc_u32 s29, s46, s29
	s_and_b64 s[36:37], s[44:45], exec
	s_cselect_b32 s19, s29, s31
	s_cselect_b32 s60, s28, s30
	s_add_u32 s0, s0, 0x80080
	s_addc_u32 s1, s1, 0
	s_add_u32 s61, s30, 0x100
	v_mov_b32_e32 v2, 0
	s_addc_u32 s62, s31, 0
	s_mov_b32 s63, -2
	v_mov_b32_e32 v3, v2
	v_mov_b32_e32 v4, v2
	v_mov_b32_e32 v5, v2
	v_mov_b32_e32 v6, v2
	v_mov_b32_e32 v7, v2
	v_mov_b32_e32 v8, v2
	v_mov_b32_e32 v9, v2
	v_mov_b32_e32 v18, v2
	v_mov_b32_e32 v19, v2
	v_mov_b32_e32 v20, v2
	v_mov_b32_e32 v21, v2
	v_mov_b32_e32 v22, v2
	v_mov_b32_e32 v23, v2
	v_mov_b32_e32 v24, v2
	v_mov_b32_e32 v25, v2
	v_mov_b32_e32 v34, v2
	v_mov_b32_e32 v35, v2
	v_mov_b32_e32 v36, v2
	v_mov_b32_e32 v37, v2
	v_mov_b32_e32 v38, v2
	v_mov_b32_e32 v39, v2
	v_mov_b32_e32 v40, v2
	v_mov_b32_e32 v41, v2
	v_mov_b32_e32 v50, v2
	v_mov_b32_e32 v51, v2
	v_mov_b32_e32 v52, v2
	v_mov_b32_e32 v53, v2
	v_mov_b32_e32 v54, v2
	v_mov_b32_e32 v55, v2
	v_mov_b32_e32 v56, v2
	v_mov_b32_e32 v57, v2
	v_mov_b32_e32 v10, v2
	v_mov_b32_e32 v11, v2
	v_mov_b32_e32 v12, v2
	v_mov_b32_e32 v13, v2
	v_mov_b32_e32 v14, v2
	v_mov_b32_e32 v15, v2
	v_mov_b32_e32 v16, v2
	v_mov_b32_e32 v17, v2
	v_mov_b32_e32 v26, v2
	v_mov_b32_e32 v27, v2
	v_mov_b32_e32 v28, v2
	v_mov_b32_e32 v29, v2
	v_mov_b32_e32 v30, v2
	v_mov_b32_e32 v31, v2
	v_mov_b32_e32 v32, v2
	v_mov_b32_e32 v33, v2
	v_mov_b32_e32 v42, v2
	v_mov_b32_e32 v43, v2
	v_mov_b32_e32 v44, v2
	v_mov_b32_e32 v45, v2
	v_mov_b32_e32 v46, v2
	v_mov_b32_e32 v47, v2
	v_mov_b32_e32 v48, v2
	v_mov_b32_e32 v49, v2
	v_mov_b32_e32 v58, v2
	v_mov_b32_e32 v59, v2
	v_mov_b32_e32 v60, v2
	v_mov_b32_e32 v61, v2
	v_mov_b32_e32 v62, v2
	v_mov_b32_e32 v63, v2
	v_mov_b32_e32 v64, v2
	v_mov_b32_e32 v65, v2
	v_mov_b32_e32 v66, v2
	v_mov_b32_e32 v67, v2
	v_mov_b32_e32 v68, v2
	v_mov_b32_e32 v69, v2
	v_mov_b32_e32 v70, v2
	v_mov_b32_e32 v71, v2
	v_mov_b32_e32 v72, v2
	v_mov_b32_e32 v73, v2
	v_mov_b32_e32 v82, v2
	v_mov_b32_e32 v83, v2
	v_mov_b32_e32 v84, v2
	v_mov_b32_e32 v85, v2
	v_mov_b32_e32 v86, v2
	v_mov_b32_e32 v87, v2
	v_mov_b32_e32 v88, v2
	v_mov_b32_e32 v89, v2
	v_mov_b32_e32 v98, v2
	v_mov_b32_e32 v99, v2
	v_mov_b32_e32 v100, v2
	v_mov_b32_e32 v101, v2
	v_mov_b32_e32 v102, v2
	v_mov_b32_e32 v103, v2
	v_mov_b32_e32 v104, v2
	v_mov_b32_e32 v105, v2
	v_mov_b32_e32 v114, v2
	v_mov_b32_e32 v115, v2
	v_mov_b32_e32 v116, v2
	v_mov_b32_e32 v117, v2
	v_mov_b32_e32 v118, v2
	v_mov_b32_e32 v119, v2
	v_mov_b32_e32 v120, v2
	v_mov_b32_e32 v121, v2
	v_mov_b32_e32 v74, v2
	v_mov_b32_e32 v75, v2
	v_mov_b32_e32 v76, v2
	v_mov_b32_e32 v77, v2
	v_mov_b32_e32 v78, v2
	v_mov_b32_e32 v79, v2
	v_mov_b32_e32 v80, v2
	v_mov_b32_e32 v81, v2
	v_mov_b32_e32 v90, v2
	v_mov_b32_e32 v91, v2
	v_mov_b32_e32 v92, v2
	v_mov_b32_e32 v93, v2
	v_mov_b32_e32 v94, v2
	v_mov_b32_e32 v95, v2
	v_mov_b32_e32 v96, v2
	v_mov_b32_e32 v97, v2
	v_mov_b32_e32 v106, v2
	v_mov_b32_e32 v107, v2
	v_mov_b32_e32 v108, v2
	v_mov_b32_e32 v109, v2
	v_mov_b32_e32 v110, v2
	v_mov_b32_e32 v111, v2
	v_mov_b32_e32 v112, v2
	v_mov_b32_e32 v113, v2
	v_mov_b32_e32 v122, v2
	v_mov_b32_e32 v123, v2
	v_mov_b32_e32 v124, v2
	v_mov_b32_e32 v125, v2
	v_mov_b32_e32 v126, v2
	v_mov_b32_e32 v127, v2
	v_mov_b32_e32 v128, v2
	v_mov_b32_e32 v129, v2
	v_add_u32_e32 v244, 0x10000, v199
	v_add_u32_e32 v245, 0x14000, v199
	v_add_u32_e32 v246, 0x18000, v199
	v_add_u32_e32 v247, 0x1c000, v199
.LBB0_667:
	s_add_u32 s30, s0, 0xfff80080
	s_addc_u32 s31, s1, -1
	s_add_i32 s66, 0, 0x10000
	s_cmp_eq_u32 s63, 28
	s_cselect_b32 s37, s23, s31
	s_cselect_b32 s36, s59, s30
	s_cselect_b32 s31, s19, s62
	s_cselect_b32 s30, s60, s61
	s_add_i32 s68, 0, 0x14000
	ds_read_b128 v[130:133], v244
	ds_read_b128 v[134:137], v244 offset:1024
	ds_read_b128 v[138:141], v244 offset:2048
	ds_read_b128 v[142:145], v244 offset:3072
	ds_read_b128 v[146:149], v245
	ds_read_b128 v[150:153], v245 offset:1024
	ds_read_b128 v[154:157], v245 offset:2048
	ds_read_b128 v[162:165], v245 offset:3072
	s_add_u32 s98, s0, 0xfff80000
	s_addc_u32 s99, s1, -1
	s_mov_b32 m0, s54
	s_nop 0
	global_load_lds_dwordx4 v172, s[98:99]
	s_mov_b32 m0, s55
	s_nop 0
	global_load_lds_dwordx4 v174, s[98:99]
	s_add_i32 m0, s48, 0xc000
	ds_read_b128 v[176:179], v201
	ds_read_b128 v[180:183], v201 offset:1024
	ds_read_b128 v[184:187], v201 offset:2048
	ds_read_b128 v[188:191], v201 offset:3072
	ds_read_b128 v[202:205], v201 offset:4096
	ds_read_b128 v[206:209], v201 offset:5120
	ds_read_b128 v[210:213], v201 offset:6144
	ds_read_b128 v[214:217], v201 offset:7168
	global_load_lds_dwordx4 v172, s[0:1]
	s_add_i32 m0, s48, 0xe000
	s_nop 0
	global_load_lds_dwordx4 v174, s[0:1]
	s_waitcnt vmcnt(8)
	s_waitcnt lgkmcnt(0)
	s_barrier
; #define PG8_STAGE(bufoff, gbase, voff) do { _Pragma("unroll") for (int _i = 0; _i < 2; ++_i) \
;         __builtin_amdgcn_global_load_lds((const unsigned*)((const char*)(gbase) + (voff)[_i]), (PG8_LAS unsigned*)(lds + (bufoff) + ldsw + _i * 8192), 16, 0, 0); } while (0)
; #define PG8_LDA(dst, b, h) do { _Pragma("unroll") for (int m = 0; m < 4; ++m) _Pragma("unroll") for (int k = 0; k < 2; ++k) dst[m][k] = *(const PG8_LAS bf16x8*)(lds + PG8_SA(b, h) + aoff + m * 2048 + k * 1024); } while (0)
; #define PG8_LDB(dst, b, h) do { _Pragma("unroll") for (int n = 0; n < 2; ++n) _Pragma("unroll") for (int k = 0; k < 2; ++k) dst[n][k] = *(const PG8_LAS bf16x8*)(lds + PG8_SB(b, h) + boff + n * 2048 + k * 1024); } while (0)
; #define PG8_MMA(ai, bj, At, Bt) do { __builtin_amdgcn_s_setprio(1); _Pragma("unroll") for (int m = 0; m < 4; ++m) _Pragma("unroll") for (int n = 0; n < 2; ++n) _Pragma("unroll") for (int k = 0; k < 2; ++k) \
;         acc[ai][bj][m][n] = __builtin_amdgcn_mfma_f32_16x16x32_bf16(Bt[n][k], At[m][k], acc[ai][bj][m][n], 0, 0, 0); __builtin_amdgcn_s_setprio(0); } while (0)
; #define PG8_WAIT_V(n) asm volatile("s_waitcnt vmcnt(" #n ")" ::: "memory")
; #define PG8_WAIT_L(n) asm volatile("s_waitcnt lgkmcnt(" #n ")" ::: "memory")
; #define PG8_BAR __builtin_amdgcn_s_barrier()
; #define PG8_SCHED __builtin_amdgcn_sched_barrier(0)
; template <class Epi, class Sched, bool ALIGN_EPI = false, bool SP2 = false>
; __device__ __forceinline__ void gemm_phase(PG8_LAS unsigned char* lds, const Gemm g, const Sched& S, const Epi& E) {
;     ...
;             PG8_WAIT_V(8); PG8_WAIT_L(0); PG8_BAR; PG8_MMA(0, 0, At, B0); PG8_MMA(0, 1, At, B1); PG8_BAR; PG8_SCHED;
;             PG8_LDA(At, 0, 1); PG8_STAGE(PG8_SB(0, 0), b2, voffB); PG8_STAGE(PG8_SB(0, 1), b2 + hstep, voffB); PG8_STAGE(PG8_SA(0, 0), a2, voffA);
;             PG8_WAIT_V(8); PG8_WAIT_L(0); PG8_BAR; PG8_MMA(1, 0, At, B0); PG8_MMA(1, 1, At, B1); PG8_BAR; PG8_SCHED;
;             PG8_LDB(B0, 1, 0); PG8_LDB(B1, 1, 1); PG8_SCHED; PG8_LDA(At, 1, 0); PG8_STAGE(PG8_SA(0, 1), a2 + hstep, voffA);
	s_waitcnt lgkmcnt(0)
	v_mfma_f32_16x16x32_bf16 v[126:129], v[130:133], v[176:179], v[126:129]
	v_mfma_f32_16x16x32_bf16 v[122:125], v[138:141], v[176:179], v[122:125]
	v_mfma_f32_16x16x32_bf16 v[110:113], v[130:133], v[184:187], v[110:113]
	v_mfma_f32_16x16x32_bf16 v[106:109], v[138:141], v[184:187], v[106:109]
	v_mfma_f32_16x16x32_bf16 v[94:97], v[130:133], v[202:205], v[94:97]
	v_mfma_f32_16x16x32_bf16 v[90:93], v[138:141], v[202:205], v[90:93]
	v_mfma_f32_16x16x32_bf16 v[78:81], v[130:133], v[210:213], v[78:81]
	v_mfma_f32_16x16x32_bf16 v[74:77], v[138:141], v[210:213], v[74:77]
	v_mfma_f32_16x16x32_bf16 v[126:129], v[134:137], v[180:183], v[126:129]
	v_mfma_f32_16x16x32_bf16 v[122:125], v[142:145], v[180:183], v[122:125]
	v_mfma_f32_16x16x32_bf16 v[110:113], v[134:137], v[188:191], v[110:113]
	v_mfma_f32_16x16x32_bf16 v[106:109], v[142:145], v[188:191], v[106:109]
	v_mfma_f32_16x16x32_bf16 v[94:97], v[134:137], v[206:209], v[94:97]
	v_mfma_f32_16x16x32_bf16 v[90:93], v[142:145], v[206:209], v[90:93]
	v_mfma_f32_16x16x32_bf16 v[78:81], v[134:137], v[214:217], v[78:81]
	v_mfma_f32_16x16x32_bf16 v[74:77], v[142:145], v[214:217], v[74:77]
	v_mfma_f32_16x16x32_bf16 v[118:121], v[146:149], v[176:179], v[118:121]
	v_mfma_f32_16x16x32_bf16 v[114:117], v[154:157], v[176:179], v[114:117]
	v_mfma_f32_16x16x32_bf16 v[102:105], v[146:149], v[184:187], v[102:105]
	v_mfma_f32_16x16x32_bf16 v[98:101], v[154:157], v[184:187], v[98:101]
	v_mfma_f32_16x16x32_bf16 v[86:89], v[146:149], v[202:205], v[86:89]
	v_mfma_f32_16x16x32_bf16 v[82:85], v[154:157], v[202:205], v[82:85]
	v_mfma_f32_16x16x32_bf16 v[70:73], v[146:149], v[210:213], v[70:73]
	v_mfma_f32_16x16x32_bf16 v[66:69], v[154:157], v[210:213], v[66:69]
	v_mfma_f32_16x16x32_bf16 v[118:121], v[150:153], v[180:183], v[118:121]
	v_mfma_f32_16x16x32_bf16 v[114:117], v[162:165], v[180:183], v[114:117]
	v_mfma_f32_16x16x32_bf16 v[102:105], v[150:153], v[188:191], v[102:105]
	v_mfma_f32_16x16x32_bf16 v[98:101], v[162:165], v[188:191], v[98:101]
	v_mfma_f32_16x16x32_bf16 v[86:89], v[150:153], v[206:209], v[86:89]
	v_mfma_f32_16x16x32_bf16 v[82:85], v[162:165], v[206:209], v[82:85]
	v_mfma_f32_16x16x32_bf16 v[70:73], v[150:153], v[214:217], v[70:73]
	v_mfma_f32_16x16x32_bf16 v[66:69], v[162:165], v[214:217], v[66:69]
	s_barrier
	s_add_i32 s66, s66, s47
	s_mov_b32 m0, s66
	ds_read_b128 v[176:179], v201 offset:16384
	ds_read_b128 v[180:183], v201 offset:17408
	ds_read_b128 v[184:187], v201 offset:18432
	ds_read_b128 v[188:191], v201 offset:19456
	ds_read_b128 v[202:205], v201 offset:20480
	ds_read_b128 v[206:209], v201 offset:21504
	ds_read_b128 v[210:213], v201 offset:22528
	ds_read_b128 v[214:217], v201 offset:23552
	global_load_lds_dwordx4 v158, s[30:31]
	s_add_i32 m0, s66, 0x2000
	s_add_u32 s66, s30, 0x80000
	s_addc_u32 s67, s31, 0
	s_add_i32 s68, s68, s47
	global_load_lds_dwordx4 v166, s[30:31]
	s_mov_b32 m0, s68
	s_nop 0
	global_load_lds_dwordx4 v158, s[66:67]
	s_add_i32 m0, s68, 0x2000
	s_nop 0
	global_load_lds_dwordx4 v166, s[66:67]
	s_waitcnt vmcnt(6)
	s_waitcnt lgkmcnt(0)
	s_barrier
	s_waitcnt lgkmcnt(0)
	v_mfma_f32_16x16x32_bf16 v[62:65], v[130:133], v[176:179], v[62:65]
	v_mfma_f32_16x16x32_bf16 v[58:61], v[138:141], v[176:179], v[58:61]
	v_mfma_f32_16x16x32_bf16 v[46:49], v[130:133], v[184:187], v[46:49]
	v_mfma_f32_16x16x32_bf16 v[42:45], v[138:141], v[184:187], v[42:45]
	v_mfma_f32_16x16x32_bf16 v[30:33], v[130:133], v[202:205], v[30:33]
	v_mfma_f32_16x16x32_bf16 v[26:29], v[138:141], v[202:205], v[26:29]
	v_mfma_f32_16x16x32_bf16 v[14:17], v[130:133], v[210:213], v[14:17]
	v_mfma_f32_16x16x32_bf16 v[10:13], v[138:141], v[210:213], v[10:13]
	v_mfma_f32_16x16x32_bf16 v[62:65], v[134:137], v[180:183], v[62:65]
	v_mfma_f32_16x16x32_bf16 v[58:61], v[142:145], v[180:183], v[58:61]
	v_mfma_f32_16x16x32_bf16 v[46:49], v[134:137], v[188:191], v[46:49]
	v_mfma_f32_16x16x32_bf16 v[42:45], v[142:145], v[188:191], v[42:45]
	v_mfma_f32_16x16x32_bf16 v[30:33], v[134:137], v[206:209], v[30:33]
	v_mfma_f32_16x16x32_bf16 v[26:29], v[142:145], v[206:209], v[26:29]
	v_mfma_f32_16x16x32_bf16 v[14:17], v[134:137], v[214:217], v[14:17]
	v_mfma_f32_16x16x32_bf16 v[10:13], v[142:145], v[214:217], v[10:13]
	v_mfma_f32_16x16x32_bf16 v[54:57], v[146:149], v[176:179], v[54:57]
	v_mfma_f32_16x16x32_bf16 v[50:53], v[154:157], v[176:179], v[50:53]
	v_mfma_f32_16x16x32_bf16 v[38:41], v[146:149], v[184:187], v[38:41]
	v_mfma_f32_16x16x32_bf16 v[34:37], v[154:157], v[184:187], v[34:37]
	v_mfma_f32_16x16x32_bf16 v[22:25], v[146:149], v[202:205], v[22:25]
	v_mfma_f32_16x16x32_bf16 v[18:21], v[154:157], v[202:205], v[18:21]
	v_mfma_f32_16x16x32_bf16 v[6:9], v[146:149], v[210:213], v[6:9]
	v_mfma_f32_16x16x32_bf16 v[2:5], v[154:157], v[210:213], v[2:5]
	v_mfma_f32_16x16x32_bf16 v[54:57], v[150:153], v[180:183], v[54:57]
	v_mfma_f32_16x16x32_bf16 v[50:53], v[162:165], v[180:183], v[50:53]
	v_mfma_f32_16x16x32_bf16 v[38:41], v[150:153], v[188:191], v[38:41]
	v_mfma_f32_16x16x32_bf16 v[34:37], v[162:165], v[188:191], v[34:37]
	v_mfma_f32_16x16x32_bf16 v[22:25], v[150:153], v[206:209], v[22:25]
	v_mfma_f32_16x16x32_bf16 v[18:21], v[162:165], v[206:209], v[18:21]
	v_mfma_f32_16x16x32_bf16 v[6:9], v[150:153], v[214:217], v[6:9]
	v_mfma_f32_16x16x32_bf16 v[2:5], v[162:165], v[214:217], v[2:5]
	s_barrier
; #define PG8_STAGE(bufoff, gbase, voff) do { _Pragma("unroll") for (int _i = 0; _i < 2; ++_i) \
;         __builtin_amdgcn_global_load_lds((const unsigned*)((const char*)(gbase) + (voff)[_i]), (PG8_LAS unsigned*)(lds + (bufoff) + ldsw + _i * 8192), 16, 0, 0); } while (0)
; #define PG8_LDA(dst, b, h) do { _Pragma("unroll") for (int m = 0; m < 4; ++m) _Pragma("unroll") for (int k = 0; k < 2; ++k) dst[m][k] = *(const PG8_LAS bf16x8*)(lds + PG8_SA(b, h) + aoff + m * 2048 + k * 1024); } while (0)
; #define PG8_LDB(dst, b, h) do { _Pragma("unroll") for (int n = 0; n < 2; ++n) _Pragma("unroll") for (int k = 0; k < 2; ++k) dst[n][k] = *(const PG8_LAS bf16x8*)(lds + PG8_SB(b, h) + boff + n * 2048 + k * 1024); } while (0)
; #define PG8_MMA(ai, bj, At, Bt) do { __builtin_amdgcn_s_setprio(1); _Pragma("unroll") for (int m = 0; m < 4; ++m) _Pragma("unroll") for (int n = 0; n < 2; ++n) _Pragma("unroll") for (int k = 0; k < 2; ++k) \
;         acc[ai][bj][m][n] = __builtin_amdgcn_mfma_f32_16x16x32_bf16(Bt[n][k], At[m][k], acc[ai][bj][m][n], 0, 0, 0); __builtin_amdgcn_s_setprio(0); } while (0)
; #define PG8_WAIT_V(n) asm volatile("s_waitcnt vmcnt(" #n ")" ::: "memory")
; #define PG8_WAIT_L(n) asm volatile("s_waitcnt lgkmcnt(" #n ")" ::: "memory")
; #define PG8_BAR __builtin_amdgcn_s_barrier()
; #define PG8_SCHED __builtin_amdgcn_sched_barrier(0)
; template <class Epi, class Sched, bool ALIGN_EPI = false, bool SP2 = false>
; __device__ __forceinline__ void gemm_phase(PG8_LAS unsigned char* lds, const Gemm g, const Sched& S, const Epi& E) {
;     ...
;             PG8_LDB(B0, 1, 0); PG8_LDB(B1, 1, 1); PG8_SCHED; PG8_LDA(At, 1, 0); PG8_STAGE(PG8_SA(0, 1), a2 + hstep, voffA);
;             PG8_WAIT_V(8); PG8_WAIT_L(0); PG8_BAR; PG8_MMA(0, 0, At, B0); PG8_MMA(0, 1, At, B1); PG8_BAR; PG8_SCHED;
;             PG8_LDA(At, 1, 1); PG8_STAGE(PG8_SB(1, 0), b3, voffB); PG8_STAGE(PG8_SB(1, 1), b3 + hstep, voffB); PG8_STAGE(PG8_SA(1, 0), a3, voffA);
;             PG8_WAIT_V(8); PG8_WAIT_L(0); PG8_BAR; PG8_MMA(1, 0, At, B0); PG8_MMA(1, 1, At, B1); PG8_BAR; PG8_SCHED;
	s_add_i32 s66, 0, 0x18000
	s_add_i32 s67, 0, 0x1c000
	ds_read_b128 v[130:133], v246
	ds_read_b128 v[134:137], v246 offset:1024
	ds_read_b128 v[138:141], v246 offset:2048
	ds_read_b128 v[142:145], v246 offset:3072
	ds_read_b128 v[146:149], v247
	ds_read_b128 v[150:153], v247 offset:1024
	ds_read_b128 v[154:157], v247 offset:2048
	ds_read_b128 v[162:165], v247 offset:3072
	s_mov_b32 m0, s48
	s_nop 0
	global_load_lds_dwordx4 v170, s[36:37]
	s_mov_b32 m0, s49
	s_nop 0
	global_load_lds_dwordx4 v168, s[36:37]
	s_add_u32 s36, s36, 0x80000
	s_addc_u32 s37, s37, 0
	s_mov_b32 m0, s50
	ds_read_b128 v[176:179], v201 offset:32768
	ds_read_b128 v[180:183], v201 offset:33792
	ds_read_b128 v[184:187], v201 offset:34816
	ds_read_b128 v[188:191], v201 offset:35840
	ds_read_b128 v[202:205], v201 offset:36864
	ds_read_b128 v[206:209], v201 offset:37888
	ds_read_b128 v[210:213], v201 offset:38912
	ds_read_b128 v[214:217], v201 offset:39936
	global_load_lds_dwordx4 v170, s[36:37]
	s_mov_b32 m0, s51
	s_nop 0
	global_load_lds_dwordx4 v168, s[36:37]
	s_waitcnt vmcnt(8)
	s_waitcnt lgkmcnt(0)
	s_barrier
	s_waitcnt lgkmcnt(0)
	v_mfma_f32_16x16x32_bf16 v[126:129], v[130:133], v[176:179], v[126:129]
	v_mfma_f32_16x16x32_bf16 v[122:125], v[138:141], v[176:179], v[122:125]
	v_mfma_f32_16x16x32_bf16 v[110:113], v[130:133], v[184:187], v[110:113]
	v_mfma_f32_16x16x32_bf16 v[106:109], v[138:141], v[184:187], v[106:109]
	v_mfma_f32_16x16x32_bf16 v[94:97], v[130:133], v[202:205], v[94:97]
	v_mfma_f32_16x16x32_bf16 v[90:93], v[138:141], v[202:205], v[90:93]
	v_mfma_f32_16x16x32_bf16 v[78:81], v[130:133], v[210:213], v[78:81]
	v_mfma_f32_16x16x32_bf16 v[74:77], v[138:141], v[210:213], v[74:77]
	v_mfma_f32_16x16x32_bf16 v[126:129], v[134:137], v[180:183], v[126:129]
	v_mfma_f32_16x16x32_bf16 v[122:125], v[142:145], v[180:183], v[122:125]
	v_mfma_f32_16x16x32_bf16 v[110:113], v[134:137], v[188:191], v[110:113]
	v_mfma_f32_16x16x32_bf16 v[106:109], v[142:145], v[188:191], v[106:109]
	v_mfma_f32_16x16x32_bf16 v[94:97], v[134:137], v[206:209], v[94:97]
	v_mfma_f32_16x16x32_bf16 v[90:93], v[142:145], v[206:209], v[90:93]
	v_mfma_f32_16x16x32_bf16 v[78:81], v[134:137], v[214:217], v[78:81]
	v_mfma_f32_16x16x32_bf16 v[74:77], v[142:145], v[214:217], v[74:77]
	v_mfma_f32_16x16x32_bf16 v[118:121], v[146:149], v[176:179], v[118:121]
	v_mfma_f32_16x16x32_bf16 v[114:117], v[154:157], v[176:179], v[114:117]
	v_mfma_f32_16x16x32_bf16 v[102:105], v[146:149], v[184:187], v[102:105]
	v_mfma_f32_16x16x32_bf16 v[98:101], v[154:157], v[184:187], v[98:101]
	v_mfma_f32_16x16x32_bf16 v[86:89], v[146:149], v[202:205], v[86:89]
	v_mfma_f32_16x16x32_bf16 v[82:85], v[154:157], v[202:205], v[82:85]
	v_mfma_f32_16x16x32_bf16 v[70:73], v[146:149], v[210:213], v[70:73]
	v_mfma_f32_16x16x32_bf16 v[66:69], v[154:157], v[210:213], v[66:69]
	v_mfma_f32_16x16x32_bf16 v[118:121], v[150:153], v[180:183], v[118:121]
	v_mfma_f32_16x16x32_bf16 v[114:117], v[162:165], v[180:183], v[114:117]
	v_mfma_f32_16x16x32_bf16 v[102:105], v[150:153], v[188:191], v[102:105]
	v_mfma_f32_16x16x32_bf16 v[98:101], v[162:165], v[188:191], v[98:101]
	v_mfma_f32_16x16x32_bf16 v[86:89], v[150:153], v[206:209], v[86:89]
	v_mfma_f32_16x16x32_bf16 v[82:85], v[162:165], v[206:209], v[82:85]
	v_mfma_f32_16x16x32_bf16 v[70:73], v[150:153], v[214:217], v[70:73]
	v_mfma_f32_16x16x32_bf16 v[66:69], v[162:165], v[214:217], v[66:69]
	s_barrier
	s_add_i32 s36, s66, s47
	s_add_i32 m0, s36, 0xffffff80
	ds_read_b128 v[176:179], v201 offset:49152
	ds_read_b128 v[180:183], v201 offset:50176
	ds_read_b128 v[184:187], v201 offset:51200
	ds_read_b128 v[188:191], v201 offset:52224
	ds_read_b128 v[202:205], v201 offset:53248
	ds_read_b128 v[206:209], v201 offset:54272
	ds_read_b128 v[210:213], v201 offset:55296
	ds_read_b128 v[214:217], v201 offset:56320
	global_load_lds_dwordx4 v158, s[30:31] offset:128
	s_add_i32 m0, s36, 0x1f80
	s_add_i32 s36, s67, s47
	global_load_lds_dwordx4 v166, s[30:31] offset:128
	s_add_u32 s30, s30, 0x80080
	s_addc_u32 s31, s31, 0
	s_mov_b32 m0, s36
	s_nop 0
	global_load_lds_dwordx4 v158, s[30:31]
	s_add_i32 m0, s36, 0x2000
	s_nop 0
	global_load_lds_dwordx4 v166, s[30:31]
	s_waitcnt vmcnt(6)
	s_waitcnt lgkmcnt(0)
	s_barrier
	s_waitcnt lgkmcnt(0)
	v_mfma_f32_16x16x32_bf16 v[62:65], v[130:133], v[176:179], v[62:65]
	v_mfma_f32_16x16x32_bf16 v[58:61], v[138:141], v[176:179], v[58:61]
	v_mfma_f32_16x16x32_bf16 v[46:49], v[130:133], v[184:187], v[46:49]
	v_mfma_f32_16x16x32_bf16 v[42:45], v[138:141], v[184:187], v[42:45]
	v_mfma_f32_16x16x32_bf16 v[30:33], v[130:133], v[202:205], v[30:33]
	v_mfma_f32_16x16x32_bf16 v[26:29], v[138:141], v[202:205], v[26:29]
	v_mfma_f32_16x16x32_bf16 v[14:17], v[130:133], v[210:213], v[14:17]
	v_mfma_f32_16x16x32_bf16 v[10:13], v[138:141], v[210:213], v[10:13]
	v_mfma_f32_16x16x32_bf16 v[62:65], v[134:137], v[180:183], v[62:65]
	v_mfma_f32_16x16x32_bf16 v[58:61], v[142:145], v[180:183], v[58:61]
	v_mfma_f32_16x16x32_bf16 v[46:49], v[134:137], v[188:191], v[46:49]
	v_mfma_f32_16x16x32_bf16 v[42:45], v[142:145], v[188:191], v[42:45]
	v_mfma_f32_16x16x32_bf16 v[30:33], v[134:137], v[206:209], v[30:33]
	v_mfma_f32_16x16x32_bf16 v[26:29], v[142:145], v[206:209], v[26:29]
	v_mfma_f32_16x16x32_bf16 v[14:17], v[134:137], v[214:217], v[14:17]
	v_mfma_f32_16x16x32_bf16 v[10:13], v[142:145], v[214:217], v[10:13]
	v_mfma_f32_16x16x32_bf16 v[54:57], v[146:149], v[176:179], v[54:57]
	v_mfma_f32_16x16x32_bf16 v[50:53], v[154:157], v[176:179], v[50:53]
	v_mfma_f32_16x16x32_bf16 v[38:41], v[146:149], v[184:187], v[38:41]
	v_mfma_f32_16x16x32_bf16 v[34:37], v[154:157], v[184:187], v[34:37]
	v_mfma_f32_16x16x32_bf16 v[22:25], v[146:149], v[202:205], v[22:25]
	v_mfma_f32_16x16x32_bf16 v[18:21], v[154:157], v[202:205], v[18:21]
	v_mfma_f32_16x16x32_bf16 v[6:9], v[146:149], v[210:213], v[6:9]
	v_mfma_f32_16x16x32_bf16 v[2:5], v[154:157], v[210:213], v[2:5]
	v_mfma_f32_16x16x32_bf16 v[54:57], v[150:153], v[180:183], v[54:57]
	v_mfma_f32_16x16x32_bf16 v[50:53], v[162:165], v[180:183], v[50:53]
	v_mfma_f32_16x16x32_bf16 v[38:41], v[150:153], v[188:191], v[38:41]
	v_mfma_f32_16x16x32_bf16 v[34:37], v[162:165], v[188:191], v[34:37]
	v_mfma_f32_16x16x32_bf16 v[22:25], v[150:153], v[206:209], v[22:25]
	v_mfma_f32_16x16x32_bf16 v[18:21], v[162:165], v[206:209], v[18:21]
	v_mfma_f32_16x16x32_bf16 v[6:9], v[150:153], v[214:217], v[6:9]
	v_mfma_f32_16x16x32_bf16 v[2:5], v[162:165], v[214:217], v[2:5]
	s_barrier
	s_add_i32 s63, s63, 2
	s_add_u32 s0, s0, 0x100
	s_addc_u32 s1, s1, 0
	s_add_u32 s61, s61, 0x100
	s_addc_u32 s62, s62, 0
	s_cmp_gt_u32 s63, 29
	s_cbranch_scc0 .LBB0_667
	s_and_b64 vcc, exec, s[16:17]
	s_cbranch_vccz .LBB0_670
	s_barrier

; #define PG8_STAGE(bufoff, gbase, voff) do { _Pragma("unroll") for (int _i = 0; _i < 2; ++_i) \
;         __builtin_amdgcn_global_load_lds((const unsigned*)((const char*)(gbase) + (voff)[_i]), (PG8_LAS unsigned*)(lds + (bufoff) + ldsw + _i * 8192), 16, 0, 0); } while (0)
; #define PG8_LDA(dst, b, h) do { _Pragma("unroll") for (int m = 0; m < 4; ++m) _Pragma("unroll") for (int k = 0; k < 2; ++k) dst[m][k] = *(const PG8_LAS bf16x8*)(lds + PG8_SA(b, h) + aoff + m * 2048 + k * 1024); } while (0)
; #define PG8_LDB(dst, b, h) do { _Pragma("unroll") for (int n = 0; n < 2; ++n) _Pragma("unroll") for (int k = 0; k < 2; ++k) dst[n][k] = *(const PG8_LAS bf16x8*)(lds + PG8_SB(b, h) + boff + n * 2048 + k * 1024); } while (0)
; #define PG8_WAIT_V(n) asm volatile("s_waitcnt vmcnt(" #n ")" ::: "memory")
; #define PG8_WAIT_L(n) asm volatile("s_waitcnt lgkmcnt(" #n ")" ::: "memory")
; #define PG8_BAR __builtin_amdgcn_s_barrier()
; #define PG8_SCHED __builtin_amdgcn_sched_barrier(0)
; template <class Epi, class Sched, bool ALIGN_EPI = false, bool SP2 = false>
; __device__ __forceinline__ void gemm_phase(PG8_LAS unsigned char* lds, const Gemm g, const Sched& S, const Epi& E) {
;     ...
;         const char* nA = has_next ? (const char*)g.A + (size_t)nxt.pm * tstep : cA; const char* nB = has_next ? (const char*)g.Bt + (size_t)nxt.pn * tstep : cB;
;         for (int t = 0; t < nt; t += 2) {
;             const bool last = (t == nt - 2);
;             const char* a1 = cA + (size_t)(t + 1) * kstep;
;             const char* a2 = last ? nA : cA + (size_t)(t + 2) * kstep; const char* b2 = last ? nB : cB + (size_t)(t + 2) * kstep;
;             const char* a3 = a2 + kstep; const char* b3 = b2 + kstep;
;             if (last && has_next) S.a_ready(nxt);
;             if constexpr (SP2) {
;             PG8_LDB(B0, 0, 0); PG8_LDB(B1, 0, 1); PG8_SCHED; PG8_LDA(At, 0, 0); PG8_STAGE(PG8_SA(1, 1), a1 + hstep, voffA);
;             PG8_WAIT_V(8); PG8_WAIT_L(0); PG8_BAR; PG8_MMA(0, 0, At, B0); PG8_MMA(0, 1, At, B1); PG8_BAR; PG8_SCHED;
;     ...
; #pragma unroll
;         for (int a = 0; a < 2; ++a)
; #pragma unroll
;             for (int b = 0; b < 2; ++b)
; #pragma unroll
;                 for (int m = 0; m < 4; ++m)
; #pragma unroll
;                     for (int n = 0; n < 2; ++n) acc[a][b][m][n] = (f32x4){0.f, 0.f, 0.f, 0.f};
;         cur = nxt; cA = nA; cB = nB; ++ui;
.LBB0_761:
	s_ashr_i32 s23, s22, 31
	s_lshl_b64 s[0:1], s[22:23], 20
	s_add_u32 s24, s21, s0
	s_addc_u32 s25, s34, s1
	s_and_b64 s[0:1], s[44:45], exec
	s_cselect_b32 s23, s25, s37
	s_cselect_b32 s60, s24, s36
	s_ashr_i32 s19, s18, 31
	s_lshl_b64 s[0:1], s[18:19], 20
	s_add_u32 s28, s38, s0
	s_addc_u32 s29, s39, s1
	s_and_b64 s[0:1], s[44:45], exec
	s_cselect_b32 s19, s29, s31
	s_cselect_b32 s61, s28, s30
	s_add_u32 s0, s36, 0x80080
	s_addc_u32 s1, s37, 0
	s_add_u32 s62, s30, 0x100
	v_mov_b32_e32 v2, 0
	s_addc_u32 s63, s31, 0
	s_mov_b32 s66, -2
	v_mov_b32_e32 v3, v2
	v_mov_b32_e32 v4, v2
	v_mov_b32_e32 v5, v2
	v_mov_b32_e32 v6, v2
	v_mov_b32_e32 v7, v2
	v_mov_b32_e32 v8, v2
	v_mov_b32_e32 v9, v2
	v_mov_b32_e32 v18, v2
	v_mov_b32_e32 v19, v2
	v_mov_b32_e32 v20, v2
	v_mov_b32_e32 v21, v2
	v_mov_b32_e32 v22, v2
	v_mov_b32_e32 v23, v2
	v_mov_b32_e32 v24, v2
	v_mov_b32_e32 v25, v2
	v_mov_b32_e32 v34, v2
	v_mov_b32_e32 v35, v2
	v_mov_b32_e32 v36, v2
	v_mov_b32_e32 v37, v2
	v_mov_b32_e32 v38, v2
	v_mov_b32_e32 v39, v2
	v_mov_b32_e32 v40, v2
	v_mov_b32_e32 v41, v2
	v_mov_b32_e32 v50, v2
	v_mov_b32_e32 v51, v2
	v_mov_b32_e32 v52, v2
	v_mov_b32_e32 v53, v2
	v_mov_b32_e32 v54, v2
	v_mov_b32_e32 v55, v2
	v_mov_b32_e32 v56, v2
	v_mov_b32_e32 v57, v2
	v_mov_b32_e32 v10, v2
	v_mov_b32_e32 v11, v2
	v_mov_b32_e32 v12, v2
	v_mov_b32_e32 v13, v2
	v_mov_b32_e32 v14, v2
	v_mov_b32_e32 v15, v2
	v_mov_b32_e32 v16, v2
	v_mov_b32_e32 v17, v2
	v_mov_b32_e32 v26, v2
	v_mov_b32_e32 v27, v2
	v_mov_b32_e32 v28, v2
	v_mov_b32_e32 v29, v2
	v_mov_b32_e32 v30, v2
	v_mov_b32_e32 v31, v2
	v_mov_b32_e32 v32, v2
	v_mov_b32_e32 v33, v2
	v_mov_b32_e32 v42, v2
	v_mov_b32_e32 v43, v2
	v_mov_b32_e32 v44, v2
	v_mov_b32_e32 v45, v2
	v_mov_b32_e32 v46, v2
	v_mov_b32_e32 v47, v2
	v_mov_b32_e32 v48, v2
	v_mov_b32_e32 v49, v2
	v_mov_b32_e32 v58, v2
	v_mov_b32_e32 v59, v2
	v_mov_b32_e32 v60, v2
	v_mov_b32_e32 v61, v2
	v_mov_b32_e32 v62, v2
	v_mov_b32_e32 v63, v2
	v_mov_b32_e32 v64, v2
	v_mov_b32_e32 v65, v2
	v_mov_b32_e32 v66, v2
	v_mov_b32_e32 v67, v2
	v_mov_b32_e32 v68, v2
	v_mov_b32_e32 v69, v2
	v_mov_b32_e32 v70, v2
	v_mov_b32_e32 v71, v2
	v_mov_b32_e32 v72, v2
	v_mov_b32_e32 v73, v2
	v_mov_b32_e32 v82, v2
	v_mov_b32_e32 v83, v2
	v_mov_b32_e32 v84, v2
	v_mov_b32_e32 v85, v2
	v_mov_b32_e32 v86, v2
	v_mov_b32_e32 v87, v2
	v_mov_b32_e32 v88, v2
	v_mov_b32_e32 v89, v2
	v_mov_b32_e32 v98, v2
	v_mov_b32_e32 v99, v2
	v_mov_b32_e32 v100, v2
	v_mov_b32_e32 v101, v2
	v_mov_b32_e32 v102, v2
	v_mov_b32_e32 v103, v2
	v_mov_b32_e32 v104, v2
	v_mov_b32_e32 v105, v2
	v_mov_b32_e32 v114, v2
	v_mov_b32_e32 v115, v2
	v_mov_b32_e32 v116, v2
	v_mov_b32_e32 v117, v2
	v_mov_b32_e32 v118, v2
	v_mov_b32_e32 v119, v2
	v_mov_b32_e32 v120, v2
	v_mov_b32_e32 v121, v2
	v_mov_b32_e32 v74, v2
	v_mov_b32_e32 v75, v2
	v_mov_b32_e32 v76, v2
	v_mov_b32_e32 v77, v2
	v_mov_b32_e32 v78, v2
	v_mov_b32_e32 v79, v2
	v_mov_b32_e32 v80, v2
	v_mov_b32_e32 v81, v2
	v_mov_b32_e32 v90, v2
	v_mov_b32_e32 v91, v2
	v_mov_b32_e32 v92, v2
	v_mov_b32_e32 v93, v2
	v_mov_b32_e32 v94, v2
	v_mov_b32_e32 v95, v2
	v_mov_b32_e32 v96, v2
	v_mov_b32_e32 v97, v2
	v_mov_b32_e32 v106, v2
	v_mov_b32_e32 v107, v2
	v_mov_b32_e32 v108, v2
	v_mov_b32_e32 v109, v2
	v_mov_b32_e32 v110, v2
	v_mov_b32_e32 v111, v2
	v_mov_b32_e32 v112, v2
	v_mov_b32_e32 v113, v2
	v_mov_b32_e32 v122, v2
	v_mov_b32_e32 v123, v2
	v_mov_b32_e32 v124, v2
	v_mov_b32_e32 v125, v2
	v_mov_b32_e32 v126, v2
	v_mov_b32_e32 v127, v2
	v_mov_b32_e32 v128, v2
	v_mov_b32_e32 v129, v2
	v_add_u32_e32 v244, 0x10000, v146
	v_add_u32_e32 v245, 0x14000, v146
	v_add_u32_e32 v246, 0x18000, v146
	v_add_u32_e32 v247, 0x1c000, v146
.LBB0_762:
	s_add_u32 s30, s0, 0xfff80080
	s_addc_u32 s31, s1, -1
	s_add_i32 s67, 0, 0x10000
	s_cmp_eq_u32 s66, 28
	s_cselect_b32 s37, s23, s31
	s_cselect_b32 s36, s60, s30
	s_cselect_b32 s31, s19, s63
	s_cselect_b32 s30, s61, s62
	s_add_i32 s70, 0, 0x14000
	ds_read_b128 v[140:143], v244
	ds_read_b128 v[152:155], v244 offset:1024
	ds_read_b128 v[162:165], v244 offset:2048
	ds_read_b128 v[166:169], v244 offset:3072
	ds_read_b128 v[170:173], v245
	ds_read_b128 v[174:177], v245 offset:1024
	ds_read_b128 v[178:181], v245 offset:2048
	ds_read_b128 v[182:185], v245 offset:3072
	s_add_u32 s98, s0, 0xfff80000
	s_addc_u32 s99, s1, -1
	s_mov_b32 m0, s52
	s_nop 0
	global_load_lds_dwordx4 v136, s[98:99]
	s_mov_b32 m0, s53
	s_nop 0
	global_load_lds_dwordx4 v138, s[98:99]
	s_add_i32 m0, s47, 0xc000
	ds_read_b128 v[186:189], v150
	ds_read_b128 v[190:193], v150 offset:1024
	ds_read_b128 v[200:203], v150 offset:2048
	ds_read_b128 v[204:207], v150 offset:3072
	ds_read_b128 v[208:211], v150 offset:4096
	ds_read_b128 v[212:215], v150 offset:5120
	ds_read_b128 v[216:219], v150 offset:6144
	ds_read_b128 v[220:223], v150 offset:7168
	global_load_lds_dwordx4 v136, s[0:1]
	s_add_i32 m0, s47, 0xe000
	s_nop 0
	global_load_lds_dwordx4 v138, s[0:1]
	s_waitcnt vmcnt(8)
	s_waitcnt lgkmcnt(0)
	s_barrier
; #define PG8_STAGE(bufoff, gbase, voff) do { _Pragma("unroll") for (int _i = 0; _i < 2; ++_i) \
;         __builtin_amdgcn_global_load_lds((const unsigned*)((const char*)(gbase) + (voff)[_i]), (PG8_LAS unsigned*)(lds + (bufoff) + ldsw + _i * 8192), 16, 0, 0); } while (0)
; #define PG8_LDA(dst, b, h) do { _Pragma("unroll") for (int m = 0; m < 4; ++m) _Pragma("unroll") for (int k = 0; k < 2; ++k) dst[m][k] = *(const PG8_LAS bf16x8*)(lds + PG8_SA(b, h) + aoff + m * 2048 + k * 1024); } while (0)
; #define PG8_MMA(ai, bj, At, Bt) do { __builtin_amdgcn_s_setprio(1); _Pragma("unroll") for (int m = 0; m < 4; ++m) _Pragma("unroll") for (int n = 0; n < 2; ++n) _Pragma("unroll") for (int k = 0; k < 2; ++k) \
;         acc[ai][bj][m][n] = __builtin_amdgcn_mfma_f32_16x16x32_bf16(Bt[n][k], At[m][k], acc[ai][bj][m][n], 0, 0, 0); __builtin_amdgcn_s_setprio(0); } while (0)
; #define PG8_WAIT_V(n) asm volatile("s_waitcnt vmcnt(" #n ")" ::: "memory")
; #define PG8_WAIT_L(n) asm volatile("s_waitcnt lgkmcnt(" #n ")" ::: "memory")
; #define PG8_BAR __builtin_amdgcn_s_barrier()
; #define PG8_SCHED __builtin_amdgcn_sched_barrier(0)
; template <class Epi, class Sched, bool ALIGN_EPI = false, bool SP2 = false>
; __device__ __forceinline__ void gemm_phase(PG8_LAS unsigned char* lds, const Gemm g, const Sched& S, const Epi& E) {
;     ...
;             PG8_WAIT_V(8); PG8_WAIT_L(0); PG8_BAR; PG8_MMA(0, 0, At, B0); PG8_MMA(0, 1, At, B1); PG8_BAR; PG8_SCHED;
;             PG8_LDA(At, 0, 1); PG8_STAGE(PG8_SB(0, 0), b2, voffB); PG8_STAGE(PG8_SB(0, 1), b2 + hstep, voffB); PG8_STAGE(PG8_SA(0, 0), a2, voffA);
;             PG8_WAIT_V(8); PG8_WAIT_L(0); PG8_BAR; PG8_MMA(1, 0, At, B0); PG8_MMA(1, 1, At, B1); PG8_BAR; PG8_SCHED;
	s_waitcnt lgkmcnt(0)
	v_mfma_f32_16x16x32_bf16 v[126:129], v[140:143], v[186:189], v[126:129]
	v_mfma_f32_16x16x32_bf16 v[122:125], v[162:165], v[186:189], v[122:125]
	v_mfma_f32_16x16x32_bf16 v[110:113], v[140:143], v[200:203], v[110:113]
	v_mfma_f32_16x16x32_bf16 v[106:109], v[162:165], v[200:203], v[106:109]
	v_mfma_f32_16x16x32_bf16 v[94:97], v[140:143], v[208:211], v[94:97]
	v_mfma_f32_16x16x32_bf16 v[90:93], v[162:165], v[208:211], v[90:93]
	v_mfma_f32_16x16x32_bf16 v[78:81], v[140:143], v[216:219], v[78:81]
	v_mfma_f32_16x16x32_bf16 v[74:77], v[162:165], v[216:219], v[74:77]
	v_mfma_f32_16x16x32_bf16 v[126:129], v[152:155], v[190:193], v[126:129]
	v_mfma_f32_16x16x32_bf16 v[122:125], v[166:169], v[190:193], v[122:125]
	v_mfma_f32_16x16x32_bf16 v[110:113], v[152:155], v[204:207], v[110:113]
	v_mfma_f32_16x16x32_bf16 v[106:109], v[166:169], v[204:207], v[106:109]
	v_mfma_f32_16x16x32_bf16 v[94:97], v[152:155], v[212:215], v[94:97]
	v_mfma_f32_16x16x32_bf16 v[90:93], v[166:169], v[212:215], v[90:93]
	v_mfma_f32_16x16x32_bf16 v[78:81], v[152:155], v[220:223], v[78:81]
	v_mfma_f32_16x16x32_bf16 v[74:77], v[166:169], v[220:223], v[74:77]
	v_mfma_f32_16x16x32_bf16 v[118:121], v[170:173], v[186:189], v[118:121]
	v_mfma_f32_16x16x32_bf16 v[114:117], v[178:181], v[186:189], v[114:117]
	v_mfma_f32_16x16x32_bf16 v[102:105], v[170:173], v[200:203], v[102:105]
	v_mfma_f32_16x16x32_bf16 v[98:101], v[178:181], v[200:203], v[98:101]
	v_mfma_f32_16x16x32_bf16 v[86:89], v[170:173], v[208:211], v[86:89]
	v_mfma_f32_16x16x32_bf16 v[82:85], v[178:181], v[208:211], v[82:85]
	v_mfma_f32_16x16x32_bf16 v[70:73], v[170:173], v[216:219], v[70:73]
	v_mfma_f32_16x16x32_bf16 v[66:69], v[178:181], v[216:219], v[66:69]
	v_mfma_f32_16x16x32_bf16 v[118:121], v[174:177], v[190:193], v[118:121]
	v_mfma_f32_16x16x32_bf16 v[114:117], v[182:185], v[190:193], v[114:117]
	v_mfma_f32_16x16x32_bf16 v[102:105], v[174:177], v[204:207], v[102:105]
	v_mfma_f32_16x16x32_bf16 v[98:101], v[182:185], v[204:207], v[98:101]
	v_mfma_f32_16x16x32_bf16 v[86:89], v[174:177], v[212:215], v[86:89]
	v_mfma_f32_16x16x32_bf16 v[82:85], v[182:185], v[212:215], v[82:85]
	v_mfma_f32_16x16x32_bf16 v[70:73], v[174:177], v[220:223], v[70:73]
	v_mfma_f32_16x16x32_bf16 v[66:69], v[182:185], v[220:223], v[66:69]
	s_barrier
	s_add_i32 s67, s67, s46
	s_mov_b32 m0, s67
	ds_read_b128 v[186:189], v150 offset:16384
	ds_read_b128 v[190:193], v150 offset:17408
	ds_read_b128 v[200:203], v150 offset:18432
	ds_read_b128 v[204:207], v150 offset:19456
	ds_read_b128 v[208:211], v150 offset:20480
	ds_read_b128 v[212:215], v150 offset:21504
	ds_read_b128 v[216:219], v150 offset:22528
	ds_read_b128 v[220:223], v150 offset:23552
	global_load_lds_dwordx4 v158, s[30:31]
	s_add_i32 m0, s67, 0x2000
	s_add_u32 s68, s30, 0x80000
	s_addc_u32 s69, s31, 0
	s_add_i32 s67, s70, s46
	global_load_lds_dwordx4 v134, s[30:31]
	s_mov_b32 m0, s67
	s_nop 0
	global_load_lds_dwordx4 v158, s[68:69]
	s_add_i32 m0, s67, 0x2000
	s_nop 0
	global_load_lds_dwordx4 v134, s[68:69]
	s_waitcnt vmcnt(6)
	s_waitcnt lgkmcnt(0)
	s_barrier
	s_waitcnt lgkmcnt(0)
	v_mfma_f32_16x16x32_bf16 v[62:65], v[140:143], v[186:189], v[62:65]
	v_mfma_f32_16x16x32_bf16 v[58:61], v[162:165], v[186:189], v[58:61]
	v_mfma_f32_16x16x32_bf16 v[46:49], v[140:143], v[200:203], v[46:49]
	v_mfma_f32_16x16x32_bf16 v[42:45], v[162:165], v[200:203], v[42:45]
	v_mfma_f32_16x16x32_bf16 v[30:33], v[140:143], v[208:211], v[30:33]
	v_mfma_f32_16x16x32_bf16 v[26:29], v[162:165], v[208:211], v[26:29]
	v_mfma_f32_16x16x32_bf16 v[14:17], v[140:143], v[216:219], v[14:17]
	v_mfma_f32_16x16x32_bf16 v[10:13], v[162:165], v[216:219], v[10:13]
	v_mfma_f32_16x16x32_bf16 v[62:65], v[152:155], v[190:193], v[62:65]
	v_mfma_f32_16x16x32_bf16 v[58:61], v[166:169], v[190:193], v[58:61]
	v_mfma_f32_16x16x32_bf16 v[46:49], v[152:155], v[204:207], v[46:49]
	v_mfma_f32_16x16x32_bf16 v[42:45], v[166:169], v[204:207], v[42:45]
	v_mfma_f32_16x16x32_bf16 v[30:33], v[152:155], v[212:215], v[30:33]
	v_mfma_f32_16x16x32_bf16 v[26:29], v[166:169], v[212:215], v[26:29]
	v_mfma_f32_16x16x32_bf16 v[14:17], v[152:155], v[220:223], v[14:17]
	v_mfma_f32_16x16x32_bf16 v[10:13], v[166:169], v[220:223], v[10:13]
	v_mfma_f32_16x16x32_bf16 v[54:57], v[170:173], v[186:189], v[54:57]
	v_mfma_f32_16x16x32_bf16 v[50:53], v[178:181], v[186:189], v[50:53]
	v_mfma_f32_16x16x32_bf16 v[38:41], v[170:173], v[200:203], v[38:41]
	v_mfma_f32_16x16x32_bf16 v[34:37], v[178:181], v[200:203], v[34:37]
	v_mfma_f32_16x16x32_bf16 v[22:25], v[170:173], v[208:211], v[22:25]
	v_mfma_f32_16x16x32_bf16 v[18:21], v[178:181], v[208:211], v[18:21]
	v_mfma_f32_16x16x32_bf16 v[6:9], v[170:173], v[216:219], v[6:9]
	v_mfma_f32_16x16x32_bf16 v[2:5], v[178:181], v[216:219], v[2:5]
	v_mfma_f32_16x16x32_bf16 v[54:57], v[174:177], v[190:193], v[54:57]
	v_mfma_f32_16x16x32_bf16 v[50:53], v[182:185], v[190:193], v[50:53]
	v_mfma_f32_16x16x32_bf16 v[38:41], v[174:177], v[204:207], v[38:41]
	v_mfma_f32_16x16x32_bf16 v[34:37], v[182:185], v[204:207], v[34:37]
	v_mfma_f32_16x16x32_bf16 v[22:25], v[174:177], v[212:215], v[22:25]
	v_mfma_f32_16x16x32_bf16 v[18:21], v[182:185], v[212:215], v[18:21]
	v_mfma_f32_16x16x32_bf16 v[6:9], v[174:177], v[220:223], v[6:9]
	v_mfma_f32_16x16x32_bf16 v[2:5], v[182:185], v[220:223], v[2:5]
	s_barrier
; #define PG8_STAGE(bufoff, gbase, voff) do { _Pragma("unroll") for (int _i = 0; _i < 2; ++_i) \
;         __builtin_amdgcn_global_load_lds((const unsigned*)((const char*)(gbase) + (voff)[_i]), (PG8_LAS unsigned*)(lds + (bufoff) + ldsw + _i * 8192), 16, 0, 0); } while (0)
; #define PG8_LDA(dst, b, h) do { _Pragma("unroll") for (int m = 0; m < 4; ++m) _Pragma("unroll") for (int k = 0; k < 2; ++k) dst[m][k] = *(const PG8_LAS bf16x8*)(lds + PG8_SA(b, h) + aoff + m * 2048 + k * 1024); } while (0)
; #define PG8_LDB(dst, b, h) do { _Pragma("unroll") for (int n = 0; n < 2; ++n) _Pragma("unroll") for (int k = 0; k < 2; ++k) dst[n][k] = *(const PG8_LAS bf16x8*)(lds + PG8_SB(b, h) + boff + n * 2048 + k * 1024); } while (0)
; #define PG8_MMA(ai, bj, At, Bt) do { __builtin_amdgcn_s_setprio(1); _Pragma("unroll") for (int m = 0; m < 4; ++m) _Pragma("unroll") for (int n = 0; n < 2; ++n) _Pragma("unroll") for (int k = 0; k < 2; ++k) \
;         acc[ai][bj][m][n] = __builtin_amdgcn_mfma_f32_16x16x32_bf16(Bt[n][k], At[m][k], acc[ai][bj][m][n], 0, 0, 0); __builtin_amdgcn_s_setprio(0); } while (0)
; #define PG8_WAIT_V(n) asm volatile("s_waitcnt vmcnt(" #n ")" ::: "memory")
; #define PG8_WAIT_L(n) asm volatile("s_waitcnt lgkmcnt(" #n ")" ::: "memory")
; #define PG8_BAR __builtin_amdgcn_s_barrier()
; #define PG8_SCHED __builtin_amdgcn_sched_barrier(0)
; template <class Epi, class Sched, bool ALIGN_EPI = false, bool SP2 = false>
; __device__ __forceinline__ void gemm_phase(PG8_LAS unsigned char* lds, const Gemm g, const Sched& S, const Epi& E) {
;     ...
;             PG8_LDB(B0, 1, 0); PG8_LDB(B1, 1, 1); PG8_SCHED; PG8_LDA(At, 1, 0); PG8_STAGE(PG8_SA(0, 1), a2 + hstep, voffA);
;             PG8_WAIT_V(8); PG8_WAIT_L(0); PG8_BAR; PG8_MMA(0, 0, At, B0); PG8_MMA(0, 1, At, B1); PG8_BAR; PG8_SCHED;
;             PG8_LDA(At, 1, 1); PG8_STAGE(PG8_SB(1, 0), b3, voffB); PG8_STAGE(PG8_SB(1, 1), b3 + hstep, voffB); PG8_STAGE(PG8_SA(1, 0), a3, voffA);
;             PG8_WAIT_V(8); PG8_WAIT_L(0); PG8_BAR; PG8_MMA(1, 0, At, B0); PG8_MMA(1, 1, At, B1); PG8_BAR; PG8_SCHED;
	s_add_i32 s67, 0, 0x18000
	s_add_i32 s68, 0, 0x1c000
	ds_read_b128 v[140:143], v246
	ds_read_b128 v[152:155], v246 offset:1024
	ds_read_b128 v[162:165], v246 offset:2048
	ds_read_b128 v[166:169], v246 offset:3072
	ds_read_b128 v[170:173], v247
	ds_read_b128 v[174:177], v247 offset:1024
	ds_read_b128 v[178:181], v247 offset:2048
	ds_read_b128 v[182:185], v247 offset:3072
	s_mov_b32 m0, s47
	s_nop 0
	global_load_lds_dwordx4 v130, s[36:37]
	s_mov_b32 m0, s48
	s_nop 0
	global_load_lds_dwordx4 v132, s[36:37]
	s_add_u32 s36, s36, 0x80000
	s_addc_u32 s37, s37, 0
	s_mov_b32 m0, s49
	ds_read_b128 v[186:189], v150 offset:32768
	ds_read_b128 v[190:193], v150 offset:33792
	ds_read_b128 v[200:203], v150 offset:34816
	ds_read_b128 v[204:207], v150 offset:35840
	ds_read_b128 v[208:211], v150 offset:36864
	ds_read_b128 v[212:215], v150 offset:37888
	ds_read_b128 v[216:219], v150 offset:38912
	ds_read_b128 v[220:223], v150 offset:39936
	global_load_lds_dwordx4 v130, s[36:37]
	s_mov_b32 m0, s50
	s_nop 0
	global_load_lds_dwordx4 v132, s[36:37]
	s_waitcnt vmcnt(8)
	s_waitcnt lgkmcnt(0)
	s_barrier
	s_waitcnt lgkmcnt(0)
	v_mfma_f32_16x16x32_bf16 v[126:129], v[140:143], v[186:189], v[126:129]
	v_mfma_f32_16x16x32_bf16 v[122:125], v[162:165], v[186:189], v[122:125]
	v_mfma_f32_16x16x32_bf16 v[110:113], v[140:143], v[200:203], v[110:113]
	v_mfma_f32_16x16x32_bf16 v[106:109], v[162:165], v[200:203], v[106:109]
	v_mfma_f32_16x16x32_bf16 v[94:97], v[140:143], v[208:211], v[94:97]
	v_mfma_f32_16x16x32_bf16 v[90:93], v[162:165], v[208:211], v[90:93]
	v_mfma_f32_16x16x32_bf16 v[78:81], v[140:143], v[216:219], v[78:81]
	v_mfma_f32_16x16x32_bf16 v[74:77], v[162:165], v[216:219], v[74:77]
	v_mfma_f32_16x16x32_bf16 v[126:129], v[152:155], v[190:193], v[126:129]
	v_mfma_f32_16x16x32_bf16 v[122:125], v[166:169], v[190:193], v[122:125]
	v_mfma_f32_16x16x32_bf16 v[110:113], v[152:155], v[204:207], v[110:113]
	v_mfma_f32_16x16x32_bf16 v[106:109], v[166:169], v[204:207], v[106:109]
	v_mfma_f32_16x16x32_bf16 v[94:97], v[152:155], v[212:215], v[94:97]
	v_mfma_f32_16x16x32_bf16 v[90:93], v[166:169], v[212:215], v[90:93]
	v_mfma_f32_16x16x32_bf16 v[78:81], v[152:155], v[220:223], v[78:81]
	v_mfma_f32_16x16x32_bf16 v[74:77], v[166:169], v[220:223], v[74:77]
	v_mfma_f32_16x16x32_bf16 v[118:121], v[170:173], v[186:189], v[118:121]
	v_mfma_f32_16x16x32_bf16 v[114:117], v[178:181], v[186:189], v[114:117]
	v_mfma_f32_16x16x32_bf16 v[102:105], v[170:173], v[200:203], v[102:105]
	v_mfma_f32_16x16x32_bf16 v[98:101], v[178:181], v[200:203], v[98:101]
	v_mfma_f32_16x16x32_bf16 v[86:89], v[170:173], v[208:211], v[86:89]
	v_mfma_f32_16x16x32_bf16 v[82:85], v[178:181], v[208:211], v[82:85]
	v_mfma_f32_16x16x32_bf16 v[70:73], v[170:173], v[216:219], v[70:73]
	v_mfma_f32_16x16x32_bf16 v[66:69], v[178:181], v[216:219], v[66:69]
	v_mfma_f32_16x16x32_bf16 v[118:121], v[174:177], v[190:193], v[118:121]
	v_mfma_f32_16x16x32_bf16 v[114:117], v[182:185], v[190:193], v[114:117]
	v_mfma_f32_16x16x32_bf16 v[102:105], v[174:177], v[204:207], v[102:105]
	v_mfma_f32_16x16x32_bf16 v[98:101], v[182:185], v[204:207], v[98:101]
	v_mfma_f32_16x16x32_bf16 v[86:89], v[174:177], v[212:215], v[86:89]
	v_mfma_f32_16x16x32_bf16 v[82:85], v[182:185], v[212:215], v[82:85]
	v_mfma_f32_16x16x32_bf16 v[70:73], v[174:177], v[220:223], v[70:73]
	v_mfma_f32_16x16x32_bf16 v[66:69], v[182:185], v[220:223], v[66:69]
	s_barrier
	s_add_i32 s36, s67, s46
	s_add_i32 m0, s36, 0xffffff80
	ds_read_b128 v[186:189], v150 offset:49152
	ds_read_b128 v[190:193], v150 offset:50176
	ds_read_b128 v[200:203], v150 offset:51200
	ds_read_b128 v[204:207], v150 offset:52224
	ds_read_b128 v[208:211], v150 offset:53248
	ds_read_b128 v[212:215], v150 offset:54272
	ds_read_b128 v[216:219], v150 offset:55296
	ds_read_b128 v[220:223], v150 offset:56320
	global_load_lds_dwordx4 v158, s[30:31] offset:128
	s_add_i32 m0, s36, 0x1f80
	s_add_i32 s36, s68, s46
	global_load_lds_dwordx4 v134, s[30:31] offset:128
	s_add_u32 s30, s30, 0x80080
	s_addc_u32 s31, s31, 0
	s_mov_b32 m0, s36
	s_nop 0
	global_load_lds_dwordx4 v158, s[30:31]
	s_add_i32 m0, s36, 0x2000
	s_nop 0
	global_load_lds_dwordx4 v134, s[30:31]
	s_waitcnt vmcnt(6)
	s_waitcnt lgkmcnt(0)
	s_barrier
	s_waitcnt lgkmcnt(0)
	v_mfma_f32_16x16x32_bf16 v[62:65], v[140:143], v[186:189], v[62:65]
	v_mfma_f32_16x16x32_bf16 v[58:61], v[162:165], v[186:189], v[58:61]
	v_mfma_f32_16x16x32_bf16 v[46:49], v[140:143], v[200:203], v[46:49]
	v_mfma_f32_16x16x32_bf16 v[42:45], v[162:165], v[200:203], v[42:45]
	v_mfma_f32_16x16x32_bf16 v[30:33], v[140:143], v[208:211], v[30:33]
	v_mfma_f32_16x16x32_bf16 v[26:29], v[162:165], v[208:211], v[26:29]
	v_mfma_f32_16x16x32_bf16 v[14:17], v[140:143], v[216:219], v[14:17]
	v_mfma_f32_16x16x32_bf16 v[10:13], v[162:165], v[216:219], v[10:13]
	v_mfma_f32_16x16x32_bf16 v[62:65], v[152:155], v[190:193], v[62:65]
	v_mfma_f32_16x16x32_bf16 v[58:61], v[166:169], v[190:193], v[58:61]
	v_mfma_f32_16x16x32_bf16 v[46:49], v[152:155], v[204:207], v[46:49]
	v_mfma_f32_16x16x32_bf16 v[42:45], v[166:169], v[204:207], v[42:45]
	v_mfma_f32_16x16x32_bf16 v[30:33], v[152:155], v[212:215], v[30:33]
	v_mfma_f32_16x16x32_bf16 v[26:29], v[166:169], v[212:215], v[26:29]
	v_mfma_f32_16x16x32_bf16 v[14:17], v[152:155], v[220:223], v[14:17]
	v_mfma_f32_16x16x32_bf16 v[10:13], v[166:169], v[220:223], v[10:13]
	v_mfma_f32_16x16x32_bf16 v[54:57], v[170:173], v[186:189], v[54:57]
	v_mfma_f32_16x16x32_bf16 v[50:53], v[178:181], v[186:189], v[50:53]
	v_mfma_f32_16x16x32_bf16 v[38:41], v[170:173], v[200:203], v[38:41]
	v_mfma_f32_16x16x32_bf16 v[34:37], v[178:181], v[200:203], v[34:37]
	v_mfma_f32_16x16x32_bf16 v[22:25], v[170:173], v[208:211], v[22:25]
	v_mfma_f32_16x16x32_bf16 v[18:21], v[178:181], v[208:211], v[18:21]
	v_mfma_f32_16x16x32_bf16 v[6:9], v[170:173], v[216:219], v[6:9]
	v_mfma_f32_16x16x32_bf16 v[2:5], v[178:181], v[216:219], v[2:5]
	v_mfma_f32_16x16x32_bf16 v[54:57], v[174:177], v[190:193], v[54:57]
	v_mfma_f32_16x16x32_bf16 v[50:53], v[182:185], v[190:193], v[50:53]
	v_mfma_f32_16x16x32_bf16 v[38:41], v[174:177], v[204:207], v[38:41]
	v_mfma_f32_16x16x32_bf16 v[34:37], v[182:185], v[204:207], v[34:37]
	v_mfma_f32_16x16x32_bf16 v[22:25], v[174:177], v[212:215], v[22:25]
	v_mfma_f32_16x16x32_bf16 v[18:21], v[182:185], v[212:215], v[18:21]
	v_mfma_f32_16x16x32_bf16 v[6:9], v[174:177], v[220:223], v[6:9]
	v_mfma_f32_16x16x32_bf16 v[2:5], v[182:185], v[220:223], v[2:5]
	s_barrier
	s_add_i32 s66, s66, 2
	s_add_u32 s0, s0, 0x100
	s_addc_u32 s1, s1, 0
	s_add_u32 s62, s62, 0x100
	s_addc_u32 s63, s63, 0
	s_cmp_gt_u32 s66, 29
	s_cbranch_scc0 .LBB0_762
	s_and_b64 vcc, exec, s[16:17]
	s_mov_b64 s[60:61], s[90:91]
	s_mov_b64 s[62:63], s[88:89]
	s_cbranch_vccz .LBB0_765
	s_barrier

; #define PG8_STAGE(bufoff, gbase, voff) do { _Pragma("unroll") for (int _i = 0; _i < 2; ++_i) \
;         __builtin_amdgcn_global_load_lds((const unsigned*)((const char*)(gbase) + (voff)[_i]), (PG8_LAS unsigned*)(lds + (bufoff) + ldsw + _i * 8192), 16, 0, 0); } while (0)
; #define PG8_LDA(dst, b, h) do { _Pragma("unroll") for (int m = 0; m < 4; ++m) _Pragma("unroll") for (int k = 0; k < 2; ++k) dst[m][k] = *(const PG8_LAS bf16x8*)(lds + PG8_SA(b, h) + aoff + m * 2048 + k * 1024); } while (0)
; #define PG8_LDB(dst, b, h) do { _Pragma("unroll") for (int n = 0; n < 2; ++n) _Pragma("unroll") for (int k = 0; k < 2; ++k) dst[n][k] = *(const PG8_LAS bf16x8*)(lds + PG8_SB(b, h) + boff + n * 2048 + k * 1024); } while (0)
; #define PG8_WAIT_V(n) asm volatile("s_waitcnt vmcnt(" #n ")" ::: "memory")
; #define PG8_WAIT_L(n) asm volatile("s_waitcnt lgkmcnt(" #n ")" ::: "memory")
; #define PG8_BAR __builtin_amdgcn_s_barrier()
; #define PG8_SCHED __builtin_amdgcn_sched_barrier(0)
; template <class Epi, class Sched, bool ALIGN_EPI = false, bool SP2 = false>
; __device__ __forceinline__ void gemm_phase(PG8_LAS unsigned char* lds, const Gemm g, const Sched& S, const Epi& E) {
;     ...
;         const char* nA = has_next ? (const char*)g.A + (size_t)nxt.pm * tstep : cA; const char* nB = has_next ? (const char*)g.Bt + (size_t)nxt.pn * tstep : cB;
;         for (int t = 0; t < nt; t += 2) {
;             const bool last = (t == nt - 2);
;             const char* a1 = cA + (size_t)(t + 1) * kstep;
;             const char* a2 = last ? nA : cA + (size_t)(t + 2) * kstep; const char* b2 = last ? nB : cB + (size_t)(t + 2) * kstep;
;             const char* a3 = a2 + kstep; const char* b3 = b2 + kstep;
;             if (last && has_next) S.a_ready(nxt);
;             if constexpr (SP2) {
;             PG8_LDB(B0, 0, 0); PG8_LDB(B1, 0, 1); PG8_SCHED; PG8_LDA(At, 0, 0); PG8_STAGE(PG8_SA(1, 1), a1 + hstep, voffA);
;             PG8_WAIT_V(8); PG8_WAIT_L(0); PG8_BAR; PG8_MMA(0, 0, At, B0); PG8_MMA(0, 1, At, B1); PG8_BAR; PG8_SCHED;
;     ...
; #pragma unroll
;         for (int a = 0; a < 2; ++a)
; #pragma unroll
;             for (int b = 0; b < 2; ++b)
; #pragma unroll
;                 for (int m = 0; m < 4; ++m)
; #pragma unroll
;                     for (int n = 0; n < 2; ++n) acc[a][b][m][n] = (f32x4){0.f, 0.f, 0.f, 0.f};
;         cur = nxt; cA = nA; cB = nB; ++ui;
.LBB0_841:
	s_ashr_i32 s23, s22, 31
	s_lshl_b64 s[24:25], s[22:23], 22
	s_add_u32 s24, s38, s24
	s_addc_u32 s25, s39, s25
	s_and_b64 s[28:29], s[44:45], exec
	s_cselect_b32 s23, s25, s1
	s_cselect_b32 s61, s24, s0
	s_ashr_i32 s19, s18, 31
	s_lshl_b64 s[28:29], s[18:19], 22
	s_add_u32 s28, s48, s28
	s_addc_u32 s29, s49, s29
	s_and_b64 s[36:37], s[44:45], exec
	s_cselect_b32 s19, s29, s31
	s_cselect_b32 s62, s28, s30
	s_add_u32 s0, s0, 0x200080
	s_addc_u32 s1, s1, 0
	s_add_u32 s63, s30, 0x100
	v_mov_b32_e32 v2, 0
	s_addc_u32 s66, s31, 0
	s_mov_b32 s67, -2
	v_mov_b32_e32 v3, v2
	v_mov_b32_e32 v4, v2
	v_mov_b32_e32 v5, v2
	v_mov_b32_e32 v6, v2
	v_mov_b32_e32 v7, v2
	v_mov_b32_e32 v8, v2
	v_mov_b32_e32 v9, v2
	v_mov_b32_e32 v18, v2
	v_mov_b32_e32 v19, v2
	v_mov_b32_e32 v20, v2
	v_mov_b32_e32 v21, v2
	v_mov_b32_e32 v22, v2
	v_mov_b32_e32 v23, v2
	v_mov_b32_e32 v24, v2
	v_mov_b32_e32 v25, v2
	v_mov_b32_e32 v34, v2
	v_mov_b32_e32 v35, v2
	v_mov_b32_e32 v36, v2
	v_mov_b32_e32 v37, v2
	v_mov_b32_e32 v38, v2
	v_mov_b32_e32 v39, v2
	v_mov_b32_e32 v40, v2
	v_mov_b32_e32 v41, v2
	v_mov_b32_e32 v50, v2
	v_mov_b32_e32 v51, v2
	v_mov_b32_e32 v52, v2
	v_mov_b32_e32 v53, v2
	v_mov_b32_e32 v54, v2
	v_mov_b32_e32 v55, v2
	v_mov_b32_e32 v56, v2
	v_mov_b32_e32 v57, v2
	v_mov_b32_e32 v10, v2
	v_mov_b32_e32 v11, v2
	v_mov_b32_e32 v12, v2
	v_mov_b32_e32 v13, v2
	v_mov_b32_e32 v14, v2
	v_mov_b32_e32 v15, v2
	v_mov_b32_e32 v16, v2
	v_mov_b32_e32 v17, v2
	v_mov_b32_e32 v26, v2
	v_mov_b32_e32 v27, v2
	v_mov_b32_e32 v28, v2
	v_mov_b32_e32 v29, v2
	v_mov_b32_e32 v30, v2
	v_mov_b32_e32 v31, v2
	v_mov_b32_e32 v32, v2
	v_mov_b32_e32 v33, v2
	v_mov_b32_e32 v42, v2
	v_mov_b32_e32 v43, v2
	v_mov_b32_e32 v44, v2
	v_mov_b32_e32 v45, v2
	v_mov_b32_e32 v46, v2
	v_mov_b32_e32 v47, v2
	v_mov_b32_e32 v48, v2
	v_mov_b32_e32 v49, v2
	v_mov_b32_e32 v58, v2
	v_mov_b32_e32 v59, v2
	v_mov_b32_e32 v60, v2
	v_mov_b32_e32 v61, v2
	v_mov_b32_e32 v62, v2
	v_mov_b32_e32 v63, v2
	v_mov_b32_e32 v64, v2
	v_mov_b32_e32 v65, v2
	v_mov_b32_e32 v66, v2
	v_mov_b32_e32 v67, v2
	v_mov_b32_e32 v68, v2
	v_mov_b32_e32 v69, v2
	v_mov_b32_e32 v70, v2
	v_mov_b32_e32 v71, v2
	v_mov_b32_e32 v72, v2
	v_mov_b32_e32 v73, v2
	v_mov_b32_e32 v82, v2
	v_mov_b32_e32 v83, v2
	v_mov_b32_e32 v84, v2
	v_mov_b32_e32 v85, v2
	v_mov_b32_e32 v86, v2
	v_mov_b32_e32 v87, v2
	v_mov_b32_e32 v88, v2
	v_mov_b32_e32 v89, v2
	v_mov_b32_e32 v98, v2
	v_mov_b32_e32 v99, v2
	v_mov_b32_e32 v100, v2
	v_mov_b32_e32 v101, v2
	v_mov_b32_e32 v102, v2
	v_mov_b32_e32 v103, v2
	v_mov_b32_e32 v104, v2
	v_mov_b32_e32 v105, v2
	v_mov_b32_e32 v114, v2
	v_mov_b32_e32 v115, v2
	v_mov_b32_e32 v116, v2
	v_mov_b32_e32 v117, v2
	v_mov_b32_e32 v118, v2
	v_mov_b32_e32 v119, v2
	v_mov_b32_e32 v120, v2
	v_mov_b32_e32 v121, v2
	v_mov_b32_e32 v74, v2
	v_mov_b32_e32 v75, v2
	v_mov_b32_e32 v76, v2
	v_mov_b32_e32 v77, v2
	v_mov_b32_e32 v78, v2
	v_mov_b32_e32 v79, v2
	v_mov_b32_e32 v80, v2
	v_mov_b32_e32 v81, v2
	v_mov_b32_e32 v90, v2
	v_mov_b32_e32 v91, v2
	v_mov_b32_e32 v92, v2
	v_mov_b32_e32 v93, v2
	v_mov_b32_e32 v94, v2
	v_mov_b32_e32 v95, v2
	v_mov_b32_e32 v96, v2
	v_mov_b32_e32 v97, v2
	v_mov_b32_e32 v106, v2
	v_mov_b32_e32 v107, v2
	v_mov_b32_e32 v108, v2
	v_mov_b32_e32 v109, v2
	v_mov_b32_e32 v110, v2
	v_mov_b32_e32 v111, v2
	v_mov_b32_e32 v112, v2
	v_mov_b32_e32 v113, v2
	v_mov_b32_e32 v122, v2
	v_mov_b32_e32 v123, v2
	v_mov_b32_e32 v124, v2
	v_mov_b32_e32 v125, v2
	v_mov_b32_e32 v126, v2
	v_mov_b32_e32 v127, v2
	v_mov_b32_e32 v128, v2
	v_mov_b32_e32 v129, v2
	v_add_u32_e32 v244, 0x10000, v199
	v_add_u32_e32 v245, 0x14000, v199
	v_add_u32_e32 v246, 0x18000, v199
	v_add_u32_e32 v247, 0x1c000, v199
.LBB0_842:
	s_add_u32 s30, s0, 0xffe00080
	s_addc_u32 s31, s1, -1
	s_add_i32 s68, 0, 0x10000
	s_cmpk_eq_i32 s67, 0x7c
	s_cselect_b32 s37, s23, s31
	s_cselect_b32 s36, s61, s30
	s_cselect_b32 s31, s19, s66
	s_cselect_b32 s30, s62, s63
	s_add_i32 s70, 0, 0x14000
	ds_read_b128 v[130:133], v244
	ds_read_b128 v[134:137], v244 offset:1024
	ds_read_b128 v[138:141], v244 offset:2048
	ds_read_b128 v[142:145], v244 offset:3072
	ds_read_b128 v[146:149], v245
	ds_read_b128 v[150:153], v245 offset:1024
	ds_read_b128 v[154:157], v245 offset:2048
	ds_read_b128 v[162:165], v245 offset:3072
	s_add_u32 s98, s0, 0xffe00000
	s_addc_u32 s99, s1, -1
	s_mov_b32 m0, s56
	s_nop 0
	global_load_lds_dwordx4 v172, s[98:99]
	s_mov_b32 m0, s57
	s_nop 0
	global_load_lds_dwordx4 v174, s[98:99]
	s_add_i32 m0, s51, 0xc000
	ds_read_b128 v[176:179], v201
	ds_read_b128 v[180:183], v201 offset:1024
	ds_read_b128 v[184:187], v201 offset:2048
	ds_read_b128 v[188:191], v201 offset:3072
	ds_read_b128 v[202:205], v201 offset:4096
	ds_read_b128 v[206:209], v201 offset:5120
	ds_read_b128 v[210:213], v201 offset:6144
	ds_read_b128 v[214:217], v201 offset:7168
	global_load_lds_dwordx4 v172, s[0:1]
	s_add_i32 m0, s51, 0xe000
	s_nop 0
	global_load_lds_dwordx4 v174, s[0:1]
	s_waitcnt vmcnt(8)
	s_waitcnt lgkmcnt(0)
	s_barrier
; #define PG8_STAGE(bufoff, gbase, voff) do { _Pragma("unroll") for (int _i = 0; _i < 2; ++_i) \
;         __builtin_amdgcn_global_load_lds((const unsigned*)((const char*)(gbase) + (voff)[_i]), (PG8_LAS unsigned*)(lds + (bufoff) + ldsw + _i * 8192), 16, 0, 0); } while (0)
; #define PG8_LDA(dst, b, h) do { _Pragma("unroll") for (int m = 0; m < 4; ++m) _Pragma("unroll") for (int k = 0; k < 2; ++k) dst[m][k] = *(const PG8_LAS bf16x8*)(lds + PG8_SA(b, h) + aoff + m * 2048 + k * 1024); } while (0)
; #define PG8_MMA(ai, bj, At, Bt) do { __builtin_amdgcn_s_setprio(1); _Pragma("unroll") for (int m = 0; m < 4; ++m) _Pragma("unroll") for (int n = 0; n < 2; ++n) _Pragma("unroll") for (int k = 0; k < 2; ++k) \
;         acc[ai][bj][m][n] = __builtin_amdgcn_mfma_f32_16x16x32_bf16(Bt[n][k], At[m][k], acc[ai][bj][m][n], 0, 0, 0); __builtin_amdgcn_s_setprio(0); } while (0)
; #define PG8_WAIT_V(n) asm volatile("s_waitcnt vmcnt(" #n ")" ::: "memory")
; #define PG8_WAIT_L(n) asm volatile("s_waitcnt lgkmcnt(" #n ")" ::: "memory")
; #define PG8_BAR __builtin_amdgcn_s_barrier()
; #define PG8_SCHED __builtin_amdgcn_sched_barrier(0)
; template <class Epi, class Sched, bool ALIGN_EPI = false, bool SP2 = false>
; __device__ __forceinline__ void gemm_phase(PG8_LAS unsigned char* lds, const Gemm g, const Sched& S, const Epi& E) {
;     ...
;             PG8_WAIT_V(8); PG8_WAIT_L(0); PG8_BAR; PG8_MMA(0, 0, At, B0); PG8_MMA(0, 1, At, B1); PG8_BAR; PG8_SCHED;
;             PG8_LDA(At, 0, 1); PG8_STAGE(PG8_SB(0, 0), b2, voffB); PG8_STAGE(PG8_SB(0, 1), b2 + hstep, voffB); PG8_STAGE(PG8_SA(0, 0), a2, voffA);
;             PG8_WAIT_V(8); PG8_WAIT_L(0); PG8_BAR; PG8_MMA(1, 0, At, B0); PG8_MMA(1, 1, At, B1); PG8_BAR; PG8_SCHED;
	s_waitcnt lgkmcnt(0)
	v_mfma_f32_16x16x32_bf16 v[126:129], v[130:133], v[176:179], v[126:129]
	v_mfma_f32_16x16x32_bf16 v[122:125], v[138:141], v[176:179], v[122:125]
	v_mfma_f32_16x16x32_bf16 v[110:113], v[130:133], v[184:187], v[110:113]
	v_mfma_f32_16x16x32_bf16 v[106:109], v[138:141], v[184:187], v[106:109]
	v_mfma_f32_16x16x32_bf16 v[94:97], v[130:133], v[202:205], v[94:97]
	v_mfma_f32_16x16x32_bf16 v[90:93], v[138:141], v[202:205], v[90:93]
	v_mfma_f32_16x16x32_bf16 v[78:81], v[130:133], v[210:213], v[78:81]
	v_mfma_f32_16x16x32_bf16 v[74:77], v[138:141], v[210:213], v[74:77]
	v_mfma_f32_16x16x32_bf16 v[126:129], v[134:137], v[180:183], v[126:129]
	v_mfma_f32_16x16x32_bf16 v[122:125], v[142:145], v[180:183], v[122:125]
	v_mfma_f32_16x16x32_bf16 v[110:113], v[134:137], v[188:191], v[110:113]
	v_mfma_f32_16x16x32_bf16 v[106:109], v[142:145], v[188:191], v[106:109]
	v_mfma_f32_16x16x32_bf16 v[94:97], v[134:137], v[206:209], v[94:97]
	v_mfma_f32_16x16x32_bf16 v[90:93], v[142:145], v[206:209], v[90:93]
	v_mfma_f32_16x16x32_bf16 v[78:81], v[134:137], v[214:217], v[78:81]
	v_mfma_f32_16x16x32_bf16 v[74:77], v[142:145], v[214:217], v[74:77]
	v_mfma_f32_16x16x32_bf16 v[118:121], v[146:149], v[176:179], v[118:121]
	v_mfma_f32_16x16x32_bf16 v[114:117], v[154:157], v[176:179], v[114:117]
	v_mfma_f32_16x16x32_bf16 v[102:105], v[146:149], v[184:187], v[102:105]
	v_mfma_f32_16x16x32_bf16 v[98:101], v[154:157], v[184:187], v[98:101]
	v_mfma_f32_16x16x32_bf16 v[86:89], v[146:149], v[202:205], v[86:89]
	v_mfma_f32_16x16x32_bf16 v[82:85], v[154:157], v[202:205], v[82:85]
	v_mfma_f32_16x16x32_bf16 v[70:73], v[146:149], v[210:213], v[70:73]
	v_mfma_f32_16x16x32_bf16 v[66:69], v[154:157], v[210:213], v[66:69]
	v_mfma_f32_16x16x32_bf16 v[118:121], v[150:153], v[180:183], v[118:121]
	v_mfma_f32_16x16x32_bf16 v[114:117], v[162:165], v[180:183], v[114:117]
	v_mfma_f32_16x16x32_bf16 v[102:105], v[150:153], v[188:191], v[102:105]
	v_mfma_f32_16x16x32_bf16 v[98:101], v[162:165], v[188:191], v[98:101]
	v_mfma_f32_16x16x32_bf16 v[86:89], v[150:153], v[206:209], v[86:89]
	v_mfma_f32_16x16x32_bf16 v[82:85], v[162:165], v[206:209], v[82:85]
	v_mfma_f32_16x16x32_bf16 v[70:73], v[150:153], v[214:217], v[70:73]
	v_mfma_f32_16x16x32_bf16 v[66:69], v[162:165], v[214:217], v[66:69]
	s_barrier
	s_add_i32 s68, s68, s50
	s_mov_b32 m0, s68
	ds_read_b128 v[176:179], v201 offset:16384
	ds_read_b128 v[180:183], v201 offset:17408
	ds_read_b128 v[184:187], v201 offset:18432
	ds_read_b128 v[188:191], v201 offset:19456
	ds_read_b128 v[202:205], v201 offset:20480
	ds_read_b128 v[206:209], v201 offset:21504
	ds_read_b128 v[210:213], v201 offset:22528
	ds_read_b128 v[214:217], v201 offset:23552
	global_load_lds_dwordx4 v158, s[30:31]
	s_add_i32 m0, s68, 0x2000
	s_add_u32 s68, s30, 0x200000
	s_addc_u32 s69, s31, 0
	s_add_i32 s70, s70, s50
	global_load_lds_dwordx4 v166, s[30:31]
	s_mov_b32 m0, s70
	s_nop 0
	global_load_lds_dwordx4 v158, s[68:69]
	s_add_i32 m0, s70, 0x2000
	s_nop 0
	global_load_lds_dwordx4 v166, s[68:69]
	s_waitcnt vmcnt(6)
	s_waitcnt lgkmcnt(0)
	s_barrier
	s_waitcnt lgkmcnt(0)
	v_mfma_f32_16x16x32_bf16 v[62:65], v[130:133], v[176:179], v[62:65]
	v_mfma_f32_16x16x32_bf16 v[58:61], v[138:141], v[176:179], v[58:61]
	v_mfma_f32_16x16x32_bf16 v[46:49], v[130:133], v[184:187], v[46:49]
	v_mfma_f32_16x16x32_bf16 v[42:45], v[138:141], v[184:187], v[42:45]
	v_mfma_f32_16x16x32_bf16 v[30:33], v[130:133], v[202:205], v[30:33]
	v_mfma_f32_16x16x32_bf16 v[26:29], v[138:141], v[202:205], v[26:29]
	v_mfma_f32_16x16x32_bf16 v[14:17], v[130:133], v[210:213], v[14:17]
	v_mfma_f32_16x16x32_bf16 v[10:13], v[138:141], v[210:213], v[10:13]
	v_mfma_f32_16x16x32_bf16 v[62:65], v[134:137], v[180:183], v[62:65]
	v_mfma_f32_16x16x32_bf16 v[58:61], v[142:145], v[180:183], v[58:61]
	v_mfma_f32_16x16x32_bf16 v[46:49], v[134:137], v[188:191], v[46:49]
	v_mfma_f32_16x16x32_bf16 v[42:45], v[142:145], v[188:191], v[42:45]
	v_mfma_f32_16x16x32_bf16 v[30:33], v[134:137], v[206:209], v[30:33]
	v_mfma_f32_16x16x32_bf16 v[26:29], v[142:145], v[206:209], v[26:29]
	v_mfma_f32_16x16x32_bf16 v[14:17], v[134:137], v[214:217], v[14:17]
	v_mfma_f32_16x16x32_bf16 v[10:13], v[142:145], v[214:217], v[10:13]
	v_mfma_f32_16x16x32_bf16 v[54:57], v[146:149], v[176:179], v[54:57]
	v_mfma_f32_16x16x32_bf16 v[50:53], v[154:157], v[176:179], v[50:53]
	v_mfma_f32_16x16x32_bf16 v[38:41], v[146:149], v[184:187], v[38:41]
	v_mfma_f32_16x16x32_bf16 v[34:37], v[154:157], v[184:187], v[34:37]
	v_mfma_f32_16x16x32_bf16 v[22:25], v[146:149], v[202:205], v[22:25]
	v_mfma_f32_16x16x32_bf16 v[18:21], v[154:157], v[202:205], v[18:21]
	v_mfma_f32_16x16x32_bf16 v[6:9], v[146:149], v[210:213], v[6:9]
	v_mfma_f32_16x16x32_bf16 v[2:5], v[154:157], v[210:213], v[2:5]
	v_mfma_f32_16x16x32_bf16 v[54:57], v[150:153], v[180:183], v[54:57]
	v_mfma_f32_16x16x32_bf16 v[50:53], v[162:165], v[180:183], v[50:53]
	v_mfma_f32_16x16x32_bf16 v[38:41], v[150:153], v[188:191], v[38:41]
	v_mfma_f32_16x16x32_bf16 v[34:37], v[162:165], v[188:191], v[34:37]
	v_mfma_f32_16x16x32_bf16 v[22:25], v[150:153], v[206:209], v[22:25]
	v_mfma_f32_16x16x32_bf16 v[18:21], v[162:165], v[206:209], v[18:21]
	v_mfma_f32_16x16x32_bf16 v[6:9], v[150:153], v[214:217], v[6:9]
	v_mfma_f32_16x16x32_bf16 v[2:5], v[162:165], v[214:217], v[2:5]
	s_barrier
; #define PG8_STAGE(bufoff, gbase, voff) do { _Pragma("unroll") for (int _i = 0; _i < 2; ++_i) \
;         __builtin_amdgcn_global_load_lds((const unsigned*)((const char*)(gbase) + (voff)[_i]), (PG8_LAS unsigned*)(lds + (bufoff) + ldsw + _i * 8192), 16, 0, 0); } while (0)
; #define PG8_LDA(dst, b, h) do { _Pragma("unroll") for (int m = 0; m < 4; ++m) _Pragma("unroll") for (int k = 0; k < 2; ++k) dst[m][k] = *(const PG8_LAS bf16x8*)(lds + PG8_SA(b, h) + aoff + m * 2048 + k * 1024); } while (0)
; #define PG8_LDB(dst, b, h) do { _Pragma("unroll") for (int n = 0; n < 2; ++n) _Pragma("unroll") for (int k = 0; k < 2; ++k) dst[n][k] = *(const PG8_LAS bf16x8*)(lds + PG8_SB(b, h) + boff + n * 2048 + k * 1024); } while (0)
; #define PG8_MMA(ai, bj, At, Bt) do { __builtin_amdgcn_s_setprio(1); _Pragma("unroll") for (int m = 0; m < 4; ++m) _Pragma("unroll") for (int n = 0; n < 2; ++n) _Pragma("unroll") for (int k = 0; k < 2; ++k) \
;         acc[ai][bj][m][n] = __builtin_amdgcn_mfma_f32_16x16x32_bf16(Bt[n][k], At[m][k], acc[ai][bj][m][n], 0, 0, 0); __builtin_amdgcn_s_setprio(0); } while (0)
; #define PG8_WAIT_V(n) asm volatile("s_waitcnt vmcnt(" #n ")" ::: "memory")
; #define PG8_WAIT_L(n) asm volatile("s_waitcnt lgkmcnt(" #n ")" ::: "memory")
; #define PG8_BAR __builtin_amdgcn_s_barrier()
; #define PG8_SCHED __builtin_amdgcn_sched_barrier(0)
; template <class Epi, class Sched, bool ALIGN_EPI = false, bool SP2 = false>
; __device__ __forceinline__ void gemm_phase(PG8_LAS unsigned char* lds, const Gemm g, const Sched& S, const Epi& E) {
;     ...
;             PG8_LDB(B0, 1, 0); PG8_LDB(B1, 1, 1); PG8_SCHED; PG8_LDA(At, 1, 0); PG8_STAGE(PG8_SA(0, 1), a2 + hstep, voffA);
;             PG8_WAIT_V(8); PG8_WAIT_L(0); PG8_BAR; PG8_MMA(0, 0, At, B0); PG8_MMA(0, 1, At, B1); PG8_BAR; PG8_SCHED;
;             PG8_LDA(At, 1, 1); PG8_STAGE(PG8_SB(1, 0), b3, voffB); PG8_STAGE(PG8_SB(1, 1), b3 + hstep, voffB); PG8_STAGE(PG8_SA(1, 0), a3, voffA);
;             PG8_WAIT_V(8); PG8_WAIT_L(0); PG8_BAR; PG8_MMA(1, 0, At, B0); PG8_MMA(1, 1, At, B1); PG8_BAR; PG8_SCHED;
	s_add_i32 s68, 0, 0x18000
	s_add_i32 s69, 0, 0x1c000
	ds_read_b128 v[130:133], v246
	ds_read_b128 v[134:137], v246 offset:1024
	ds_read_b128 v[138:141], v246 offset:2048
	ds_read_b128 v[142:145], v246 offset:3072
	ds_read_b128 v[146:149], v247
	ds_read_b128 v[150:153], v247 offset:1024
	ds_read_b128 v[154:157], v247 offset:2048
	ds_read_b128 v[162:165], v247 offset:3072
	s_mov_b32 m0, s51
	s_nop 0
	global_load_lds_dwordx4 v170, s[36:37]
	s_mov_b32 m0, s52
	s_nop 0
	global_load_lds_dwordx4 v168, s[36:37]
	s_add_u32 s36, s36, 0x200000
	s_addc_u32 s37, s37, 0
	s_mov_b32 m0, s53
	ds_read_b128 v[176:179], v201 offset:32768
	ds_read_b128 v[180:183], v201 offset:33792
	ds_read_b128 v[184:187], v201 offset:34816
	ds_read_b128 v[188:191], v201 offset:35840
	ds_read_b128 v[202:205], v201 offset:36864
	ds_read_b128 v[206:209], v201 offset:37888
	ds_read_b128 v[210:213], v201 offset:38912
	ds_read_b128 v[214:217], v201 offset:39936
	global_load_lds_dwordx4 v170, s[36:37]
	s_mov_b32 m0, s54
	s_nop 0
	global_load_lds_dwordx4 v168, s[36:37]
	s_waitcnt vmcnt(8)
	s_waitcnt lgkmcnt(0)
	s_barrier
	s_waitcnt lgkmcnt(0)
	v_mfma_f32_16x16x32_bf16 v[126:129], v[130:133], v[176:179], v[126:129]
	v_mfma_f32_16x16x32_bf16 v[122:125], v[138:141], v[176:179], v[122:125]
	v_mfma_f32_16x16x32_bf16 v[110:113], v[130:133], v[184:187], v[110:113]
	v_mfma_f32_16x16x32_bf16 v[106:109], v[138:141], v[184:187], v[106:109]
	v_mfma_f32_16x16x32_bf16 v[94:97], v[130:133], v[202:205], v[94:97]
	v_mfma_f32_16x16x32_bf16 v[90:93], v[138:141], v[202:205], v[90:93]
	v_mfma_f32_16x16x32_bf16 v[78:81], v[130:133], v[210:213], v[78:81]
	v_mfma_f32_16x16x32_bf16 v[74:77], v[138:141], v[210:213], v[74:77]
	v_mfma_f32_16x16x32_bf16 v[126:129], v[134:137], v[180:183], v[126:129]
	v_mfma_f32_16x16x32_bf16 v[122:125], v[142:145], v[180:183], v[122:125]
	v_mfma_f32_16x16x32_bf16 v[110:113], v[134:137], v[188:191], v[110:113]
	v_mfma_f32_16x16x32_bf16 v[106:109], v[142:145], v[188:191], v[106:109]
	v_mfma_f32_16x16x32_bf16 v[94:97], v[134:137], v[206:209], v[94:97]
	v_mfma_f32_16x16x32_bf16 v[90:93], v[142:145], v[206:209], v[90:93]
	v_mfma_f32_16x16x32_bf16 v[78:81], v[134:137], v[214:217], v[78:81]
	v_mfma_f32_16x16x32_bf16 v[74:77], v[142:145], v[214:217], v[74:77]
	v_mfma_f32_16x16x32_bf16 v[118:121], v[146:149], v[176:179], v[118:121]
	v_mfma_f32_16x16x32_bf16 v[114:117], v[154:157], v[176:179], v[114:117]
	v_mfma_f32_16x16x32_bf16 v[102:105], v[146:149], v[184:187], v[102:105]
	v_mfma_f32_16x16x32_bf16 v[98:101], v[154:157], v[184:187], v[98:101]
	v_mfma_f32_16x16x32_bf16 v[86:89], v[146:149], v[202:205], v[86:89]
	v_mfma_f32_16x16x32_bf16 v[82:85], v[154:157], v[202:205], v[82:85]
	v_mfma_f32_16x16x32_bf16 v[70:73], v[146:149], v[210:213], v[70:73]
	v_mfma_f32_16x16x32_bf16 v[66:69], v[154:157], v[210:213], v[66:69]
	v_mfma_f32_16x16x32_bf16 v[118:121], v[150:153], v[180:183], v[118:121]
	v_mfma_f32_16x16x32_bf16 v[114:117], v[162:165], v[180:183], v[114:117]
	v_mfma_f32_16x16x32_bf16 v[102:105], v[150:153], v[188:191], v[102:105]
	v_mfma_f32_16x16x32_bf16 v[98:101], v[162:165], v[188:191], v[98:101]
	v_mfma_f32_16x16x32_bf16 v[86:89], v[150:153], v[206:209], v[86:89]
	v_mfma_f32_16x16x32_bf16 v[82:85], v[162:165], v[206:209], v[82:85]
	v_mfma_f32_16x16x32_bf16 v[70:73], v[150:153], v[214:217], v[70:73]
	v_mfma_f32_16x16x32_bf16 v[66:69], v[162:165], v[214:217], v[66:69]
	s_barrier
	s_add_i32 s36, s68, s50
	s_add_i32 m0, s36, 0xffffff80
	ds_read_b128 v[176:179], v201 offset:49152
	ds_read_b128 v[180:183], v201 offset:50176
	ds_read_b128 v[184:187], v201 offset:51200
	ds_read_b128 v[188:191], v201 offset:52224
	ds_read_b128 v[202:205], v201 offset:53248
	ds_read_b128 v[206:209], v201 offset:54272
	ds_read_b128 v[210:213], v201 offset:55296
	ds_read_b128 v[214:217], v201 offset:56320
	global_load_lds_dwordx4 v158, s[30:31] offset:128
	s_add_i32 m0, s36, 0x1f80
	s_add_i32 s36, s69, s50
	global_load_lds_dwordx4 v166, s[30:31] offset:128
	s_add_u32 s30, s30, 0x200080
	s_addc_u32 s31, s31, 0
	s_mov_b32 m0, s36
	s_nop 0
	global_load_lds_dwordx4 v158, s[30:31]
	s_add_i32 m0, s36, 0x2000
	s_nop 0
	global_load_lds_dwordx4 v166, s[30:31]
	s_waitcnt vmcnt(6)
	s_waitcnt lgkmcnt(0)
	s_barrier
	s_waitcnt lgkmcnt(0)
	v_mfma_f32_16x16x32_bf16 v[62:65], v[130:133], v[176:179], v[62:65]
	v_mfma_f32_16x16x32_bf16 v[58:61], v[138:141], v[176:179], v[58:61]
	v_mfma_f32_16x16x32_bf16 v[46:49], v[130:133], v[184:187], v[46:49]
	v_mfma_f32_16x16x32_bf16 v[42:45], v[138:141], v[184:187], v[42:45]
	v_mfma_f32_16x16x32_bf16 v[30:33], v[130:133], v[202:205], v[30:33]
	v_mfma_f32_16x16x32_bf16 v[26:29], v[138:141], v[202:205], v[26:29]
	v_mfma_f32_16x16x32_bf16 v[14:17], v[130:133], v[210:213], v[14:17]
	v_mfma_f32_16x16x32_bf16 v[10:13], v[138:141], v[210:213], v[10:13]
	v_mfma_f32_16x16x32_bf16 v[62:65], v[134:137], v[180:183], v[62:65]
	v_mfma_f32_16x16x32_bf16 v[58:61], v[142:145], v[180:183], v[58:61]
	v_mfma_f32_16x16x32_bf16 v[46:49], v[134:137], v[188:191], v[46:49]
	v_mfma_f32_16x16x32_bf16 v[42:45], v[142:145], v[188:191], v[42:45]
	v_mfma_f32_16x16x32_bf16 v[30:33], v[134:137], v[206:209], v[30:33]
	v_mfma_f32_16x16x32_bf16 v[26:29], v[142:145], v[206:209], v[26:29]
	v_mfma_f32_16x16x32_bf16 v[14:17], v[134:137], v[214:217], v[14:17]
	v_mfma_f32_16x16x32_bf16 v[10:13], v[142:145], v[214:217], v[10:13]
	v_mfma_f32_16x16x32_bf16 v[54:57], v[146:149], v[176:179], v[54:57]
	v_mfma_f32_16x16x32_bf16 v[50:53], v[154:157], v[176:179], v[50:53]
	v_mfma_f32_16x16x32_bf16 v[38:41], v[146:149], v[184:187], v[38:41]
	v_mfma_f32_16x16x32_bf16 v[34:37], v[154:157], v[184:187], v[34:37]
	v_mfma_f32_16x16x32_bf16 v[22:25], v[146:149], v[202:205], v[22:25]
	v_mfma_f32_16x16x32_bf16 v[18:21], v[154:157], v[202:205], v[18:21]
	v_mfma_f32_16x16x32_bf16 v[6:9], v[146:149], v[210:213], v[6:9]
	v_mfma_f32_16x16x32_bf16 v[2:5], v[154:157], v[210:213], v[2:5]
	v_mfma_f32_16x16x32_bf16 v[54:57], v[150:153], v[180:183], v[54:57]
	v_mfma_f32_16x16x32_bf16 v[50:53], v[162:165], v[180:183], v[50:53]
	v_mfma_f32_16x16x32_bf16 v[38:41], v[150:153], v[188:191], v[38:41]
	v_mfma_f32_16x16x32_bf16 v[34:37], v[162:165], v[188:191], v[34:37]
	v_mfma_f32_16x16x32_bf16 v[22:25], v[150:153], v[206:209], v[22:25]
	v_mfma_f32_16x16x32_bf16 v[18:21], v[162:165], v[206:209], v[18:21]
	v_mfma_f32_16x16x32_bf16 v[6:9], v[150:153], v[214:217], v[6:9]
	v_mfma_f32_16x16x32_bf16 v[2:5], v[162:165], v[214:217], v[2:5]
	s_barrier
	s_add_i32 s67, s67, 2
	s_add_u32 s0, s0, 0x100
	s_addc_u32 s1, s1, 0
	s_add_u32 s63, s63, 0x100
	s_addc_u32 s66, s66, 0
	s_cmpk_gt_u32 s67, 0x7d
	s_cbranch_scc0 .LBB0_842
	s_and_b64 vcc, exec, s[16:17]
	s_cbranch_vccz .LBB0_845
	s_barrier

; #define PG8_STAGE(bufoff, gbase, voff) do { _Pragma("unroll") for (int _i = 0; _i < 2; ++_i) \
;         __builtin_amdgcn_global_load_lds((const unsigned*)((const char*)(gbase) + (voff)[_i]), (PG8_LAS unsigned*)(lds + (bufoff) + ldsw + _i * 8192), 16, 0, 0); } while (0)
; #define PG8_LDA(dst, b, h) do { _Pragma("unroll") for (int m = 0; m < 4; ++m) _Pragma("unroll") for (int k = 0; k < 2; ++k) dst[m][k] = *(const PG8_LAS bf16x8*)(lds + PG8_SA(b, h) + aoff + m * 2048 + k * 1024); } while (0)
; #define PG8_LDB(dst, b, h) do { _Pragma("unroll") for (int n = 0; n < 2; ++n) _Pragma("unroll") for (int k = 0; k < 2; ++k) dst[n][k] = *(const PG8_LAS bf16x8*)(lds + PG8_SB(b, h) + boff + n * 2048 + k * 1024); } while (0)
; #define PG8_WAIT_V(n) asm volatile("s_waitcnt vmcnt(" #n ")" ::: "memory")
; #define PG8_WAIT_L(n) asm volatile("s_waitcnt lgkmcnt(" #n ")" ::: "memory")
; #define PG8_BAR __builtin_amdgcn_s_barrier()
; #define PG8_SCHED __builtin_amdgcn_sched_barrier(0)
; template <class Epi, class Sched, bool ALIGN_EPI = false, bool SP2 = false>
; __device__ __forceinline__ void gemm_phase(PG8_LAS unsigned char* lds, const Gemm g, const Sched& S, const Epi& E) {
;     ...
;         const char* nA = has_next ? (const char*)g.A + (size_t)nxt.pm * tstep : cA; const char* nB = has_next ? (const char*)g.Bt + (size_t)nxt.pn * tstep : cB;
;         for (int t = 0; t < nt; t += 2) {
;             const bool last = (t == nt - 2);
;             const char* a1 = cA + (size_t)(t + 1) * kstep;
;             const char* a2 = last ? nA : cA + (size_t)(t + 2) * kstep; const char* b2 = last ? nB : cB + (size_t)(t + 2) * kstep;
;             const char* a3 = a2 + kstep; const char* b3 = b2 + kstep;
;             if (last && has_next) S.a_ready(nxt);
;             if constexpr (SP2) {
;             PG8_LDB(B0, 0, 0); PG8_LDB(B1, 0, 1); PG8_SCHED; PG8_LDA(At, 0, 0); PG8_STAGE(PG8_SA(1, 1), a1 + hstep, voffA);
;             PG8_WAIT_V(8); PG8_WAIT_L(0); PG8_BAR; PG8_MMA(0, 0, At, B0); PG8_MMA(0, 1, At, B1); PG8_BAR; PG8_SCHED;
;     ...
; #pragma unroll
;         for (int a = 0; a < 2; ++a)
; #pragma unroll
;             for (int b = 0; b < 2; ++b)
; #pragma unroll
;                 for (int m = 0; m < 4; ++m)
; #pragma unroll
;                     for (int n = 0; n < 2; ++n) acc[a][b][m][n] = (f32x4){0.f, 0.f, 0.f, 0.f};
;         cur = nxt; cA = nA; cB = nB; ++ui;
.LBB0_879:
	s_ashr_i32 s19, s18, 31
	s_lshl_b64 s[22:23], s[18:19], 22
	s_add_u32 s22, s38, s22
	s_addc_u32 s23, s39, s23
	s_and_b64 s[24:25], s[40:41], exec
	s_cselect_b32 s19, s23, s1
	s_cselect_b32 s54, s22, s0
	s_ashr_i32 s17, s16, 31
	s_lshl_b64 s[24:25], s[16:17], 22
	s_add_u32 s24, s48, s24
	s_addc_u32 s25, s49, s25
	s_and_b64 s[30:31], s[40:41], exec
	s_cselect_b32 s17, s25, s29
	s_cselect_b32 s55, s24, s28
	s_add_u32 s0, s0, 0x200080
	s_addc_u32 s1, s1, 0
	s_add_u32 s56, s28, 0x100
	v_mov_b32_e32 v2, 0
	s_addc_u32 s57, s29, 0
	s_mov_b32 s58, -2
	v_mov_b32_e32 v3, v2
	v_mov_b32_e32 v4, v2
	v_mov_b32_e32 v5, v2
	v_mov_b32_e32 v6, v2
	v_mov_b32_e32 v7, v2
	v_mov_b32_e32 v8, v2
	v_mov_b32_e32 v9, v2
	v_mov_b32_e32 v14, v2
	v_mov_b32_e32 v15, v2
	v_mov_b32_e32 v16, v2
	v_mov_b32_e32 v17, v2
	v_mov_b32_e32 v22, v2
	v_mov_b32_e32 v23, v2
	v_mov_b32_e32 v24, v2
	v_mov_b32_e32 v25, v2
	v_mov_b32_e32 v30, v2
	v_mov_b32_e32 v31, v2
	v_mov_b32_e32 v32, v2
	v_mov_b32_e32 v33, v2
	v_mov_b32_e32 v38, v2
	v_mov_b32_e32 v39, v2
	v_mov_b32_e32 v40, v2
	v_mov_b32_e32 v41, v2
	v_mov_b32_e32 v46, v2
	v_mov_b32_e32 v47, v2
	v_mov_b32_e32 v48, v2
	v_mov_b32_e32 v49, v2
	v_mov_b32_e32 v54, v2
	v_mov_b32_e32 v55, v2
	v_mov_b32_e32 v56, v2
	v_mov_b32_e32 v57, v2
	v_mov_b32_e32 v10, v2
	v_mov_b32_e32 v11, v2
	v_mov_b32_e32 v12, v2
	v_mov_b32_e32 v13, v2
	v_mov_b32_e32 v18, v2
	v_mov_b32_e32 v19, v2
	v_mov_b32_e32 v20, v2
	v_mov_b32_e32 v21, v2
	v_mov_b32_e32 v26, v2
	v_mov_b32_e32 v27, v2
	v_mov_b32_e32 v28, v2
	v_mov_b32_e32 v29, v2
	v_mov_b32_e32 v34, v2
	v_mov_b32_e32 v35, v2
	v_mov_b32_e32 v36, v2
	v_mov_b32_e32 v37, v2
	v_mov_b32_e32 v42, v2
	v_mov_b32_e32 v43, v2
	v_mov_b32_e32 v44, v2
	v_mov_b32_e32 v45, v2
	v_mov_b32_e32 v50, v2
	v_mov_b32_e32 v51, v2
	v_mov_b32_e32 v52, v2
	v_mov_b32_e32 v53, v2
	v_mov_b32_e32 v58, v2
	v_mov_b32_e32 v59, v2
	v_mov_b32_e32 v60, v2
	v_mov_b32_e32 v61, v2
	v_mov_b32_e32 v62, v2
	v_mov_b32_e32 v63, v2
	v_mov_b32_e32 v64, v2
	v_mov_b32_e32 v65, v2
	v_mov_b32_e32 v66, v2
	v_mov_b32_e32 v67, v2
	v_mov_b32_e32 v68, v2
	v_mov_b32_e32 v69, v2
	v_mov_b32_e32 v70, v2
	v_mov_b32_e32 v71, v2
	v_mov_b32_e32 v72, v2
	v_mov_b32_e32 v73, v2
	v_mov_b32_e32 v78, v2
	v_mov_b32_e32 v79, v2
	v_mov_b32_e32 v80, v2
	v_mov_b32_e32 v81, v2
	v_mov_b32_e32 v86, v2
	v_mov_b32_e32 v87, v2
	v_mov_b32_e32 v88, v2
	v_mov_b32_e32 v89, v2
	v_mov_b32_e32 v98, v2
	v_mov_b32_e32 v99, v2
	v_mov_b32_e32 v100, v2
	v_mov_b32_e32 v101, v2
	v_mov_b32_e32 v102, v2
	v_mov_b32_e32 v103, v2
	v_mov_b32_e32 v104, v2
	v_mov_b32_e32 v105, v2
	v_mov_b32_e32 v106, v2
	v_mov_b32_e32 v107, v2
	v_mov_b32_e32 v108, v2
	v_mov_b32_e32 v109, v2
	v_mov_b32_e32 v110, v2
	v_mov_b32_e32 v111, v2
	v_mov_b32_e32 v112, v2
	v_mov_b32_e32 v113, v2
	v_mov_b32_e32 v74, v2
	v_mov_b32_e32 v75, v2
	v_mov_b32_e32 v76, v2
	v_mov_b32_e32 v77, v2
	v_mov_b32_e32 v82, v2
	v_mov_b32_e32 v83, v2
	v_mov_b32_e32 v84, v2
	v_mov_b32_e32 v85, v2
	v_mov_b32_e32 v90, v2
	v_mov_b32_e32 v91, v2
	v_mov_b32_e32 v92, v2
	v_mov_b32_e32 v93, v2
	v_mov_b32_e32 v94, v2
	v_mov_b32_e32 v95, v2
	v_mov_b32_e32 v96, v2
	v_mov_b32_e32 v97, v2
	v_mov_b32_e32 v114, v2
	v_mov_b32_e32 v115, v2
	v_mov_b32_e32 v116, v2
	v_mov_b32_e32 v117, v2
	v_mov_b32_e32 v118, v2
	v_mov_b32_e32 v119, v2
	v_mov_b32_e32 v120, v2
	v_mov_b32_e32 v121, v2
	v_mov_b32_e32 v122, v2
	v_mov_b32_e32 v123, v2
	v_mov_b32_e32 v124, v2
	v_mov_b32_e32 v125, v2
	v_mov_b32_e32 v126, v2
	v_mov_b32_e32 v127, v2
	v_mov_b32_e32 v128, v2
	v_mov_b32_e32 v129, v2
	v_add_u32_e32 v244, 0x10000, v178
	v_add_u32_e32 v245, 0x14000, v178
	v_add_u32_e32 v246, 0x18000, v178
	v_add_u32_e32 v247, 0x1c000, v178
.LBB0_880:
	s_add_u32 s28, s0, 0xffe00080
	s_addc_u32 s29, s1, -1
	s_add_i32 s59, 0, 0x10000
	s_cmpk_eq_i32 s58, 0x7c
	s_cselect_b32 s31, s19, s29
	s_cselect_b32 s30, s54, s28
	s_cselect_b32 s29, s17, s57
	s_cselect_b32 s28, s55, s56
	s_add_i32 s62, 0, 0x14000
	ds_read_b128 v[130:133], v244
	ds_read_b128 v[134:137], v244 offset:1024
	ds_read_b128 v[138:141], v244 offset:2048
	ds_read_b128 v[142:145], v244 offset:3072
	ds_read_b128 v[146:149], v245
	ds_read_b128 v[162:165], v245 offset:1024
	ds_read_b128 v[168:171], v245 offset:2048
	ds_read_b128 v[172:175], v245 offset:3072
	s_add_u32 s98, s0, 0xffe00000
	s_addc_u32 s99, s1, -1
	s_mov_b32 m0, s44
	s_nop 0
	global_load_lds_dwordx4 v156, s[98:99]
	s_mov_b32 m0, s45
	s_nop 0
	global_load_lds_dwordx4 v166, s[98:99]
	s_add_i32 m0, s36, 0xc000
	ds_read_b128 v[182:185], v180
	ds_read_b128 v[186:189], v180 offset:1024
	ds_read_b128 v[190:193], v180 offset:2048
	ds_read_b128 v[200:203], v180 offset:3072
	ds_read_b128 v[204:207], v180 offset:4096
	ds_read_b128 v[208:211], v180 offset:5120
	ds_read_b128 v[212:215], v180 offset:6144
	ds_read_b128 v[216:219], v180 offset:7168
	global_load_lds_dwordx4 v156, s[0:1]
	s_add_i32 m0, s36, 0xe000
	s_nop 0
	global_load_lds_dwordx4 v166, s[0:1]
	s_waitcnt vmcnt(8)
	s_waitcnt lgkmcnt(0)
	s_barrier
; #define PG8_STAGE(bufoff, gbase, voff) do { _Pragma("unroll") for (int _i = 0; _i < 2; ++_i) \
;         __builtin_amdgcn_global_load_lds((const unsigned*)((const char*)(gbase) + (voff)[_i]), (PG8_LAS unsigned*)(lds + (bufoff) + ldsw + _i * 8192), 16, 0, 0); } while (0)
; #define PG8_LDA(dst, b, h) do { _Pragma("unroll") for (int m = 0; m < 4; ++m) _Pragma("unroll") for (int k = 0; k < 2; ++k) dst[m][k] = *(const PG8_LAS bf16x8*)(lds + PG8_SA(b, h) + aoff + m * 2048 + k * 1024); } while (0)
; #define PG8_MMA(ai, bj, At, Bt) do { __builtin_amdgcn_s_setprio(1); _Pragma("unroll") for (int m = 0; m < 4; ++m) _Pragma("unroll") for (int n = 0; n < 2; ++n) _Pragma("unroll") for (int k = 0; k < 2; ++k) \
;         acc[ai][bj][m][n] = __builtin_amdgcn_mfma_f32_16x16x32_bf16(Bt[n][k], At[m][k], acc[ai][bj][m][n], 0, 0, 0); __builtin_amdgcn_s_setprio(0); } while (0)
; #define PG8_WAIT_V(n) asm volatile("s_waitcnt vmcnt(" #n ")" ::: "memory")
; #define PG8_WAIT_L(n) asm volatile("s_waitcnt lgkmcnt(" #n ")" ::: "memory")
; #define PG8_BAR __builtin_amdgcn_s_barrier()
; #define PG8_SCHED __builtin_amdgcn_sched_barrier(0)
; template <class Epi, class Sched, bool ALIGN_EPI = false, bool SP2 = false>
; __device__ __forceinline__ void gemm_phase(PG8_LAS unsigned char* lds, const Gemm g, const Sched& S, const Epi& E) {
;     ...
;             PG8_WAIT_V(8); PG8_WAIT_L(0); PG8_BAR; PG8_MMA(0, 0, At, B0); PG8_MMA(0, 1, At, B1); PG8_BAR; PG8_SCHED;
;             PG8_LDA(At, 0, 1); PG8_STAGE(PG8_SB(0, 0), b2, voffB); PG8_STAGE(PG8_SB(0, 1), b2 + hstep, voffB); PG8_STAGE(PG8_SA(0, 0), a2, voffA);
;             PG8_WAIT_V(8); PG8_WAIT_L(0); PG8_BAR; PG8_MMA(1, 0, At, B0); PG8_MMA(1, 1, At, B1); PG8_BAR; PG8_SCHED;
	s_waitcnt lgkmcnt(0)
	v_mfma_f32_16x16x32_bf16 v[126:129], v[130:133], v[182:185], v[126:129]
	v_mfma_f32_16x16x32_bf16 v[122:125], v[138:141], v[182:185], v[122:125]
	v_mfma_f32_16x16x32_bf16 v[118:121], v[130:133], v[190:193], v[118:121]
	v_mfma_f32_16x16x32_bf16 v[114:117], v[138:141], v[190:193], v[114:117]
	v_mfma_f32_16x16x32_bf16 v[94:97], v[130:133], v[204:207], v[94:97]
	v_mfma_f32_16x16x32_bf16 v[90:93], v[138:141], v[204:207], v[90:93]
	v_mfma_f32_16x16x32_bf16 v[82:85], v[130:133], v[212:215], v[82:85]
	v_mfma_f32_16x16x32_bf16 v[74:77], v[138:141], v[212:215], v[74:77]
	v_mfma_f32_16x16x32_bf16 v[126:129], v[134:137], v[186:189], v[126:129]
	v_mfma_f32_16x16x32_bf16 v[122:125], v[142:145], v[186:189], v[122:125]
	v_mfma_f32_16x16x32_bf16 v[118:121], v[134:137], v[200:203], v[118:121]
	v_mfma_f32_16x16x32_bf16 v[114:117], v[142:145], v[200:203], v[114:117]
	v_mfma_f32_16x16x32_bf16 v[94:97], v[134:137], v[208:211], v[94:97]
	v_mfma_f32_16x16x32_bf16 v[90:93], v[142:145], v[208:211], v[90:93]
	v_mfma_f32_16x16x32_bf16 v[82:85], v[134:137], v[216:219], v[82:85]
	v_mfma_f32_16x16x32_bf16 v[74:77], v[142:145], v[216:219], v[74:77]
	v_mfma_f32_16x16x32_bf16 v[110:113], v[146:149], v[182:185], v[110:113]
	v_mfma_f32_16x16x32_bf16 v[106:109], v[168:171], v[182:185], v[106:109]
	v_mfma_f32_16x16x32_bf16 v[102:105], v[146:149], v[190:193], v[102:105]
	v_mfma_f32_16x16x32_bf16 v[98:101], v[168:171], v[190:193], v[98:101]
	v_mfma_f32_16x16x32_bf16 v[86:89], v[146:149], v[204:207], v[86:89]
	v_mfma_f32_16x16x32_bf16 v[78:81], v[168:171], v[204:207], v[78:81]
	v_mfma_f32_16x16x32_bf16 v[70:73], v[146:149], v[212:215], v[70:73]
	v_mfma_f32_16x16x32_bf16 v[66:69], v[168:171], v[212:215], v[66:69]
	v_mfma_f32_16x16x32_bf16 v[110:113], v[162:165], v[186:189], v[110:113]
	v_mfma_f32_16x16x32_bf16 v[106:109], v[172:175], v[186:189], v[106:109]
	v_mfma_f32_16x16x32_bf16 v[102:105], v[162:165], v[200:203], v[102:105]
	v_mfma_f32_16x16x32_bf16 v[98:101], v[172:175], v[200:203], v[98:101]
	v_mfma_f32_16x16x32_bf16 v[86:89], v[162:165], v[208:211], v[86:89]
	v_mfma_f32_16x16x32_bf16 v[78:81], v[172:175], v[208:211], v[78:81]
	v_mfma_f32_16x16x32_bf16 v[70:73], v[162:165], v[216:219], v[70:73]
	v_mfma_f32_16x16x32_bf16 v[66:69], v[172:175], v[216:219], v[66:69]
	s_barrier
	s_add_i32 s59, s59, s34
	s_mov_b32 m0, s59
	ds_read_b128 v[182:185], v180 offset:16384
	ds_read_b128 v[186:189], v180 offset:17408
	ds_read_b128 v[190:193], v180 offset:18432
	ds_read_b128 v[200:203], v180 offset:19456
	ds_read_b128 v[204:207], v180 offset:20480
	ds_read_b128 v[208:211], v180 offset:21504
	ds_read_b128 v[212:215], v180 offset:22528
	ds_read_b128 v[216:219], v180 offset:23552
	global_load_lds_dwordx4 v158, s[28:29]
	s_add_i32 m0, s59, 0x2000
	s_add_u32 s60, s28, 0x200000
	s_addc_u32 s61, s29, 0
	s_add_i32 s59, s62, s34
	global_load_lds_dwordx4 v150, s[28:29]
	s_mov_b32 m0, s59
	s_nop 0
	global_load_lds_dwordx4 v158, s[60:61]
	s_add_i32 m0, s59, 0x2000
	s_nop 0
	global_load_lds_dwordx4 v150, s[60:61]
	s_waitcnt vmcnt(6)
	s_waitcnt lgkmcnt(0)
	s_barrier
	s_waitcnt lgkmcnt(0)
	v_mfma_f32_16x16x32_bf16 v[62:65], v[130:133], v[182:185], v[62:65]
	v_mfma_f32_16x16x32_bf16 v[58:61], v[138:141], v[182:185], v[58:61]
	v_mfma_f32_16x16x32_bf16 v[50:53], v[130:133], v[190:193], v[50:53]
	v_mfma_f32_16x16x32_bf16 v[42:45], v[138:141], v[190:193], v[42:45]
	v_mfma_f32_16x16x32_bf16 v[34:37], v[130:133], v[204:207], v[34:37]
	v_mfma_f32_16x16x32_bf16 v[26:29], v[138:141], v[204:207], v[26:29]
	v_mfma_f32_16x16x32_bf16 v[18:21], v[130:133], v[212:215], v[18:21]
	v_mfma_f32_16x16x32_bf16 v[10:13], v[138:141], v[212:215], v[10:13]
	v_mfma_f32_16x16x32_bf16 v[62:65], v[134:137], v[186:189], v[62:65]
	v_mfma_f32_16x16x32_bf16 v[58:61], v[142:145], v[186:189], v[58:61]
	v_mfma_f32_16x16x32_bf16 v[50:53], v[134:137], v[200:203], v[50:53]
	v_mfma_f32_16x16x32_bf16 v[42:45], v[142:145], v[200:203], v[42:45]
	v_mfma_f32_16x16x32_bf16 v[34:37], v[134:137], v[208:211], v[34:37]
	v_mfma_f32_16x16x32_bf16 v[26:29], v[142:145], v[208:211], v[26:29]
	v_mfma_f32_16x16x32_bf16 v[18:21], v[134:137], v[216:219], v[18:21]
	v_mfma_f32_16x16x32_bf16 v[10:13], v[142:145], v[216:219], v[10:13]
	v_mfma_f32_16x16x32_bf16 v[54:57], v[146:149], v[182:185], v[54:57]
	v_mfma_f32_16x16x32_bf16 v[46:49], v[168:171], v[182:185], v[46:49]
	v_mfma_f32_16x16x32_bf16 v[38:41], v[146:149], v[190:193], v[38:41]
	v_mfma_f32_16x16x32_bf16 v[30:33], v[168:171], v[190:193], v[30:33]
	v_mfma_f32_16x16x32_bf16 v[22:25], v[146:149], v[204:207], v[22:25]
	v_mfma_f32_16x16x32_bf16 v[14:17], v[168:171], v[204:207], v[14:17]
	v_mfma_f32_16x16x32_bf16 v[6:9], v[146:149], v[212:215], v[6:9]
	v_mfma_f32_16x16x32_bf16 v[2:5], v[168:171], v[212:215], v[2:5]
	v_mfma_f32_16x16x32_bf16 v[54:57], v[162:165], v[186:189], v[54:57]
	v_mfma_f32_16x16x32_bf16 v[46:49], v[172:175], v[186:189], v[46:49]
	v_mfma_f32_16x16x32_bf16 v[38:41], v[162:165], v[200:203], v[38:41]
	v_mfma_f32_16x16x32_bf16 v[30:33], v[172:175], v[200:203], v[30:33]
	v_mfma_f32_16x16x32_bf16 v[22:25], v[162:165], v[208:211], v[22:25]
	v_mfma_f32_16x16x32_bf16 v[14:17], v[172:175], v[208:211], v[14:17]
	v_mfma_f32_16x16x32_bf16 v[6:9], v[162:165], v[216:219], v[6:9]
	v_mfma_f32_16x16x32_bf16 v[2:5], v[172:175], v[216:219], v[2:5]
	s_barrier
; #define PG8_STAGE(bufoff, gbase, voff) do { _Pragma("unroll") for (int _i = 0; _i < 2; ++_i) \
;         __builtin_amdgcn_global_load_lds((const unsigned*)((const char*)(gbase) + (voff)[_i]), (PG8_LAS unsigned*)(lds + (bufoff) + ldsw + _i * 8192), 16, 0, 0); } while (0)
; #define PG8_LDA(dst, b, h) do { _Pragma("unroll") for (int m = 0; m < 4; ++m) _Pragma("unroll") for (int k = 0; k < 2; ++k) dst[m][k] = *(const PG8_LAS bf16x8*)(lds + PG8_SA(b, h) + aoff + m * 2048 + k * 1024); } while (0)
; #define PG8_LDB(dst, b, h) do { _Pragma("unroll") for (int n = 0; n < 2; ++n) _Pragma("unroll") for (int k = 0; k < 2; ++k) dst[n][k] = *(const PG8_LAS bf16x8*)(lds + PG8_SB(b, h) + boff + n * 2048 + k * 1024); } while (0)
; #define PG8_MMA(ai, bj, At, Bt) do { __builtin_amdgcn_s_setprio(1); _Pragma("unroll") for (int m = 0; m < 4; ++m) _Pragma("unroll") for (int n = 0; n < 2; ++n) _Pragma("unroll") for (int k = 0; k < 2; ++k) \
;         acc[ai][bj][m][n] = __builtin_amdgcn_mfma_f32_16x16x32_bf16(Bt[n][k], At[m][k], acc[ai][bj][m][n], 0, 0, 0); __builtin_amdgcn_s_setprio(0); } while (0)
; #define PG8_WAIT_V(n) asm volatile("s_waitcnt vmcnt(" #n ")" ::: "memory")
; #define PG8_WAIT_L(n) asm volatile("s_waitcnt lgkmcnt(" #n ")" ::: "memory")
; #define PG8_BAR __builtin_amdgcn_s_barrier()
; #define PG8_SCHED __builtin_amdgcn_sched_barrier(0)
; template <class Epi, class Sched, bool ALIGN_EPI = false, bool SP2 = false>
; __device__ __forceinline__ void gemm_phase(PG8_LAS unsigned char* lds, const Gemm g, const Sched& S, const Epi& E) {
;     ...
;             PG8_LDB(B0, 1, 0); PG8_LDB(B1, 1, 1); PG8_SCHED; PG8_LDA(At, 1, 0); PG8_STAGE(PG8_SA(0, 1), a2 + hstep, voffA);
;             PG8_WAIT_V(8); PG8_WAIT_L(0); PG8_BAR; PG8_MMA(0, 0, At, B0); PG8_MMA(0, 1, At, B1); PG8_BAR; PG8_SCHED;
;             PG8_LDA(At, 1, 1); PG8_STAGE(PG8_SB(1, 0), b3, voffB); PG8_STAGE(PG8_SB(1, 1), b3 + hstep, voffB); PG8_STAGE(PG8_SA(1, 0), a3, voffA);
;             PG8_WAIT_V(8); PG8_WAIT_L(0); PG8_BAR; PG8_MMA(1, 0, At, B0); PG8_MMA(1, 1, At, B1); PG8_BAR; PG8_SCHED;
	s_add_i32 s59, 0, 0x18000
	s_add_i32 s60, 0, 0x1c000
	ds_read_b128 v[130:133], v246
	ds_read_b128 v[134:137], v246 offset:1024
	ds_read_b128 v[138:141], v246 offset:2048
	ds_read_b128 v[142:145], v246 offset:3072
	ds_read_b128 v[146:149], v247
	ds_read_b128 v[162:165], v247 offset:1024
	ds_read_b128 v[168:171], v247 offset:2048
	ds_read_b128 v[172:175], v247 offset:3072
	s_mov_b32 m0, s36
	s_nop 0
	global_load_lds_dwordx4 v154, s[30:31]
	s_mov_b32 m0, s37
	s_nop 0
	global_load_lds_dwordx4 v152, s[30:31]
	s_add_u32 s30, s30, 0x200000
	s_addc_u32 s31, s31, 0
	s_mov_b32 m0, s42
	ds_read_b128 v[182:185], v180 offset:32768
	ds_read_b128 v[186:189], v180 offset:33792
	ds_read_b128 v[190:193], v180 offset:34816
	ds_read_b128 v[200:203], v180 offset:35840
	ds_read_b128 v[204:207], v180 offset:36864
	ds_read_b128 v[208:211], v180 offset:37888
	ds_read_b128 v[212:215], v180 offset:38912
	ds_read_b128 v[216:219], v180 offset:39936
	global_load_lds_dwordx4 v154, s[30:31]
	s_mov_b32 m0, s43
	s_nop 0
	global_load_lds_dwordx4 v152, s[30:31]
	s_waitcnt vmcnt(8)
	s_waitcnt lgkmcnt(0)
	s_barrier
	s_waitcnt lgkmcnt(0)
	v_mfma_f32_16x16x32_bf16 v[126:129], v[130:133], v[182:185], v[126:129]
	v_mfma_f32_16x16x32_bf16 v[122:125], v[138:141], v[182:185], v[122:125]
	v_mfma_f32_16x16x32_bf16 v[118:121], v[130:133], v[190:193], v[118:121]
	v_mfma_f32_16x16x32_bf16 v[114:117], v[138:141], v[190:193], v[114:117]
	v_mfma_f32_16x16x32_bf16 v[94:97], v[130:133], v[204:207], v[94:97]
	v_mfma_f32_16x16x32_bf16 v[90:93], v[138:141], v[204:207], v[90:93]
	v_mfma_f32_16x16x32_bf16 v[82:85], v[130:133], v[212:215], v[82:85]
	v_mfma_f32_16x16x32_bf16 v[74:77], v[138:141], v[212:215], v[74:77]
	v_mfma_f32_16x16x32_bf16 v[126:129], v[134:137], v[186:189], v[126:129]
	v_mfma_f32_16x16x32_bf16 v[122:125], v[142:145], v[186:189], v[122:125]
	v_mfma_f32_16x16x32_bf16 v[118:121], v[134:137], v[200:203], v[118:121]
	v_mfma_f32_16x16x32_bf16 v[114:117], v[142:145], v[200:203], v[114:117]
	v_mfma_f32_16x16x32_bf16 v[94:97], v[134:137], v[208:211], v[94:97]
	v_mfma_f32_16x16x32_bf16 v[90:93], v[142:145], v[208:211], v[90:93]
	v_mfma_f32_16x16x32_bf16 v[82:85], v[134:137], v[216:219], v[82:85]
	v_mfma_f32_16x16x32_bf16 v[74:77], v[142:145], v[216:219], v[74:77]
	v_mfma_f32_16x16x32_bf16 v[110:113], v[146:149], v[182:185], v[110:113]
	v_mfma_f32_16x16x32_bf16 v[106:109], v[168:171], v[182:185], v[106:109]
	v_mfma_f32_16x16x32_bf16 v[102:105], v[146:149], v[190:193], v[102:105]
	v_mfma_f32_16x16x32_bf16 v[98:101], v[168:171], v[190:193], v[98:101]
	v_mfma_f32_16x16x32_bf16 v[86:89], v[146:149], v[204:207], v[86:89]
	v_mfma_f32_16x16x32_bf16 v[78:81], v[168:171], v[204:207], v[78:81]
	v_mfma_f32_16x16x32_bf16 v[70:73], v[146:149], v[212:215], v[70:73]
	v_mfma_f32_16x16x32_bf16 v[66:69], v[168:171], v[212:215], v[66:69]
	v_mfma_f32_16x16x32_bf16 v[110:113], v[162:165], v[186:189], v[110:113]
	v_mfma_f32_16x16x32_bf16 v[106:109], v[172:175], v[186:189], v[106:109]
	v_mfma_f32_16x16x32_bf16 v[102:105], v[162:165], v[200:203], v[102:105]
	v_mfma_f32_16x16x32_bf16 v[98:101], v[172:175], v[200:203], v[98:101]
	v_mfma_f32_16x16x32_bf16 v[86:89], v[162:165], v[208:211], v[86:89]
	v_mfma_f32_16x16x32_bf16 v[78:81], v[172:175], v[208:211], v[78:81]
	v_mfma_f32_16x16x32_bf16 v[70:73], v[162:165], v[216:219], v[70:73]
	v_mfma_f32_16x16x32_bf16 v[66:69], v[172:175], v[216:219], v[66:69]
	s_barrier
	s_add_i32 s30, s59, s34
	s_add_i32 m0, s30, 0xffffff80
	ds_read_b128 v[182:185], v180 offset:49152
	ds_read_b128 v[186:189], v180 offset:50176
	ds_read_b128 v[190:193], v180 offset:51200
	ds_read_b128 v[200:203], v180 offset:52224
	ds_read_b128 v[204:207], v180 offset:53248
	ds_read_b128 v[208:211], v180 offset:54272
	ds_read_b128 v[212:215], v180 offset:55296
	ds_read_b128 v[216:219], v180 offset:56320
	global_load_lds_dwordx4 v158, s[28:29] offset:128
	s_add_i32 m0, s30, 0x1f80
	s_add_i32 s30, s60, s34
	global_load_lds_dwordx4 v150, s[28:29] offset:128
	s_add_u32 s28, s28, 0x200080
	s_addc_u32 s29, s29, 0
	s_mov_b32 m0, s30
	s_nop 0
	global_load_lds_dwordx4 v158, s[28:29]
	s_add_i32 m0, s30, 0x2000
	s_nop 0
	global_load_lds_dwordx4 v150, s[28:29]
	s_waitcnt vmcnt(6)
	s_waitcnt lgkmcnt(0)
	s_barrier
	s_waitcnt lgkmcnt(0)
	v_mfma_f32_16x16x32_bf16 v[62:65], v[130:133], v[182:185], v[62:65]
	v_mfma_f32_16x16x32_bf16 v[58:61], v[138:141], v[182:185], v[58:61]
	v_mfma_f32_16x16x32_bf16 v[50:53], v[130:133], v[190:193], v[50:53]
	v_mfma_f32_16x16x32_bf16 v[42:45], v[138:141], v[190:193], v[42:45]
	v_mfma_f32_16x16x32_bf16 v[34:37], v[130:133], v[204:207], v[34:37]
	v_mfma_f32_16x16x32_bf16 v[26:29], v[138:141], v[204:207], v[26:29]
	v_mfma_f32_16x16x32_bf16 v[18:21], v[130:133], v[212:215], v[18:21]
	v_mfma_f32_16x16x32_bf16 v[10:13], v[138:141], v[212:215], v[10:13]
	v_mfma_f32_16x16x32_bf16 v[62:65], v[134:137], v[186:189], v[62:65]
	v_mfma_f32_16x16x32_bf16 v[58:61], v[142:145], v[186:189], v[58:61]
	v_mfma_f32_16x16x32_bf16 v[50:53], v[134:137], v[200:203], v[50:53]
	v_mfma_f32_16x16x32_bf16 v[42:45], v[142:145], v[200:203], v[42:45]
	v_mfma_f32_16x16x32_bf16 v[34:37], v[134:137], v[208:211], v[34:37]
	v_mfma_f32_16x16x32_bf16 v[26:29], v[142:145], v[208:211], v[26:29]
	v_mfma_f32_16x16x32_bf16 v[18:21], v[134:137], v[216:219], v[18:21]
	v_mfma_f32_16x16x32_bf16 v[10:13], v[142:145], v[216:219], v[10:13]
	v_mfma_f32_16x16x32_bf16 v[54:57], v[146:149], v[182:185], v[54:57]
	v_mfma_f32_16x16x32_bf16 v[46:49], v[168:171], v[182:185], v[46:49]
	v_mfma_f32_16x16x32_bf16 v[38:41], v[146:149], v[190:193], v[38:41]
	v_mfma_f32_16x16x32_bf16 v[30:33], v[168:171], v[190:193], v[30:33]
	v_mfma_f32_16x16x32_bf16 v[22:25], v[146:149], v[204:207], v[22:25]
	v_mfma_f32_16x16x32_bf16 v[14:17], v[168:171], v[204:207], v[14:17]
	v_mfma_f32_16x16x32_bf16 v[6:9], v[146:149], v[212:215], v[6:9]
	v_mfma_f32_16x16x32_bf16 v[2:5], v[168:171], v[212:215], v[2:5]
	v_mfma_f32_16x16x32_bf16 v[54:57], v[162:165], v[186:189], v[54:57]
	v_mfma_f32_16x16x32_bf16 v[46:49], v[172:175], v[186:189], v[46:49]
	v_mfma_f32_16x16x32_bf16 v[38:41], v[162:165], v[200:203], v[38:41]
	v_mfma_f32_16x16x32_bf16 v[30:33], v[172:175], v[200:203], v[30:33]
	v_mfma_f32_16x16x32_bf16 v[22:25], v[162:165], v[208:211], v[22:25]
	v_mfma_f32_16x16x32_bf16 v[14:17], v[172:175], v[208:211], v[14:17]
	v_mfma_f32_16x16x32_bf16 v[6:9], v[162:165], v[216:219], v[6:9]
	v_mfma_f32_16x16x32_bf16 v[2:5], v[172:175], v[216:219], v[2:5]
	s_barrier
	s_add_i32 s58, s58, 2
	s_add_u32 s0, s0, 0x100
	s_addc_u32 s1, s1, 0
	s_add_u32 s56, s56, 0x100
	s_addc_u32 s57, s57, 0
	s_cmpk_gt_u32 s58, 0x7d
	s_cbranch_scc0 .LBB0_880
	s_and_b64 vcc, exec, s[14:15]
	s_cbranch_vccz .LBB0_883
	s_barrier
